# norm+modulate loops (4 phases): scale/shift loads of column groups 1-3 hoisted to the trip top, vmcnt waits re-derived from first consumers
# baseline (speedup 1.0000x reference)
.LBB0_69:
	s_lshl_b64 s[36:37], s[58:59], s72
	s_add_u32 s1, s62, s36
	s_addc_u32 s2, s63, s37
	s_lshl_b64 s[36:37], s[70:71], 12
	s_add_u32 s58, s1, s36
	s_addc_u32 s59, s2, s37
	global_load_dwordx4 v[32:35], v88, s[58:59]
	global_load_dwordx4 v[24:27], v88, s[58:59] offset:1024
	v_lshl_add_u64 v[44:45], s[58:59], 0, v[88:89]
	v_add_co_u32_e32 v46, vcc, s33, v44
	v_lshl_add_u64 v[20:21], v[44:45], 0, s[4:5]
	s_nop 0
	v_addc_co_u32_e32 v47, vcc, 0, v45, vcc
	global_load_dwordx4 v[28:31], v88, s[58:59] offset:2048
	global_load_dwordx4 v[68:71], v[46:47], off offset:-4096
	global_load_dwordx4 v[40:43], v[20:21], off offset:1024
	global_load_dwordx4 v[16:19], v88, s[58:59] offset:3072
	global_load_dwordx4 v[36:39], v[20:21], off offset:2048
	s_nop 0
	global_load_dwordx4 v[20:23], v[20:21], off offset:3072
	s_add_u32 s54, s20, s54
	s_addc_u32 s55, s21, s55
	v_lshl_add_u64 v[94:95], s[54:55], 0, v[88:89]
	v_add_co_u32_e32 v48, vcc, s31, v94
	v_lshl_add_u64 v[52:53], v[44:45], 0, s[6:7]
	s_nop 0
	v_addc_co_u32_e32 v49, vcc, 0, v95, vcc
	global_load_dwordx4 v[84:87], v[48:49], off
	global_load_dwordx4 v[80:83], v[46:47], off
	global_load_dwordx4 v[60:63], v[52:53], off offset:1024
	global_load_dwordx4 v[72:75], v88, s[54:55]
	v_lshl_add_u64 v[56:57], v[44:45], 0, s[8:9]
	v_add_co_u32_e32 v44, vcc, s34, v44
	s_ashr_i32 s1, s0, 31
	s_nop 0
	v_addc_co_u32_e32 v45, vcc, 0, v45, vcc
	global_load_dwordx4 v[76:79], v[44:45], off
	global_load_dwordx4 v[64:67], v[56:57], off offset:1024
	s_nop 0
	global_load_dwordx4 v[44:47], v[56:57], off offset:2048
	global_load_dwordx4 v[48:51], v[52:53], off offset:2048
	s_nop 0
	global_load_dwordx4 v[52:55], v[52:53], off offset:3072
	s_nop 0
	global_load_dwordx4 v[56:59], v[56:57], off offset:3072
	s_lshl_b64 s[58:59], s[0:1], 11
	v_readlane_b32 s36, v239, 32
	v_readlane_b32 s37, v239, 33
	s_add_u32 s58, s36, s58
	s_addc_u32 s59, s37, s59
	v_lshl_add_u64 v[94:95], v[94:95], 0, s[4:5]
	s_add_i32 s0, s0, s11
	s_cmp_lt_i32 s0, 0x9000
	v_readlane_b32 s38, v239, 34
	v_readlane_b32 s39, v239, 35
	v_readlane_b32 s40, v239, 36
	v_readlane_b32 s41, v239, 37
	v_readlane_b32 s42, v239, 38
	v_readlane_b32 s43, v239, 39
	global_load_dwordx4 v[130:133], v[94:95], off offset:1024
	global_load_dwordx4 v[134:137], v88, s[54:55] offset:1024
	global_load_dwordx4 v[138:141], v[94:95], off offset:2048
	global_load_dwordx4 v[142:145], v88, s[54:55] offset:2048
	global_load_dwordx4 v[146:149], v[94:95], off offset:3072
	global_load_dwordx4 v[150:153], v88, s[54:55] offset:3072
	s_waitcnt vmcnt(23)
	v_mov_b32_e32 v108, v33
	s_waitcnt vmcnt(22)
	v_mov_b32_e32 v109, v25
	v_mov_b32_e32 v106, v32
	v_mov_b32_e32 v107, v24
	v_pk_mul_f32 v[108:109], v[108:109], v[108:109]
	v_mov_b32_e32 v102, v34
	v_mov_b32_e32 v103, v26
	v_pk_fma_f32 v[106:107], v[106:107], v[106:107], v[108:109]
	s_waitcnt vmcnt(20)
	v_mov_b32_e32 v122, v69
	s_waitcnt vmcnt(19)
	v_mov_b32_e32 v123, v41
	v_mov_b32_e32 v104, v35
	v_mov_b32_e32 v105, v27
	v_mov_b32_e32 v120, v68
	v_mov_b32_e32 v121, v40
	v_pk_fma_f32 v[102:103], v[102:103], v[102:103], v[106:107]
	v_pk_mul_f32 v[106:107], v[122:123], v[122:123]
	v_mov_b32_e32 v108, v70
	v_mov_b32_e32 v109, v42
	v_pk_fma_f32 v[102:103], v[104:105], v[104:105], v[102:103]
	v_pk_fma_f32 v[104:105], v[120:121], v[120:121], v[106:107]
	v_mov_b32_e32 v116, v29
	s_waitcnt vmcnt(18)
	v_mov_b32_e32 v117, v17
	v_pk_fma_f32 v[104:105], v[108:109], v[108:109], v[104:105]
	s_waitcnt vmcnt(17)
	v_mov_b32_e32 v108, v37
	s_waitcnt vmcnt(16)
	v_mov_b32_e32 v109, v21
	v_mov_b32_e32 v114, v28
	v_mov_b32_e32 v115, v16
	v_mov_b32_e32 v128, v36
	v_mov_b32_e32 v129, v20
	v_pk_mul_f32 v[116:117], v[116:117], v[116:117]
	v_pk_mul_f32 v[108:109], v[108:109], v[108:109]
	v_mov_b32_e32 v110, v30
	v_mov_b32_e32 v118, v71
	v_mov_b32_e32 v119, v43
	v_mov_b32_e32 v111, v18
	v_mov_b32_e32 v124, v38
	v_mov_b32_e32 v125, v22
	v_pk_fma_f32 v[106:107], v[114:115], v[114:115], v[116:117]
	v_pk_fma_f32 v[108:109], v[128:129], v[128:129], v[108:109]
	v_mov_b32_e32 v112, v31
	v_mov_b32_e32 v113, v19
	v_mov_b32_e32 v126, v39
	v_mov_b32_e32 v127, v23
	v_pk_fma_f32 v[106:107], v[110:111], v[110:111], v[106:107]
	v_pk_fma_f32 v[104:105], v[118:119], v[118:119], v[104:105]
	v_pk_fma_f32 v[108:109], v[124:125], v[124:125], v[108:109]
	v_pk_fma_f32 v[106:107], v[112:113], v[112:113], v[106:107]
	v_pk_fma_f32 v[108:109], v[126:127], v[126:127], v[108:109]
	v_mov_b32_e32 v110, v104
	v_mov_b32_e32 v111, v102
	v_mov_b32_e32 v102, v105
	v_pk_add_f32 v[102:103], v[110:111], v[102:103]
	v_mov_b32_e32 v104, v108
	v_mov_b32_e32 v105, v106
	v_pk_add_f32 v[102:103], v[102:103], v[104:105]
	v_mov_b32_e32 v106, v109
	v_pk_add_f32 v[102:103], v[102:103], v[106:107]
	ds_bpermute_b32 v105, v96, v103
	ds_bpermute_b32 v104, v96, v102
	s_waitcnt vmcnt(14)
	v_mov_b32_e32 v112, v81
	s_waitcnt vmcnt(13)
	v_mov_b32_e32 v113, v61
	v_mov_b32_e32 v110, v80
	v_mov_b32_e32 v111, v60
	s_waitcnt lgkmcnt(0)
	v_pk_add_f32 v[102:103], v[102:103], v[104:105]
	ds_bpermute_b32 v105, v97, v103
	ds_bpermute_b32 v104, v97, v102
	v_pk_mul_f32 v[112:113], v[112:113], v[112:113]
	v_mov_b32_e32 v106, v82
	v_mov_b32_e32 v107, v62
	v_pk_fma_f32 v[110:111], v[110:111], v[110:111], v[112:113]
	s_waitcnt lgkmcnt(0)
	v_pk_add_f32 v[102:103], v[102:103], v[104:105]
	ds_bpermute_b32 v105, v98, v103
	ds_bpermute_b32 v104, v98, v102
	s_waitcnt vmcnt(11)
	v_mov_b32_e32 v114, v77
	s_waitcnt vmcnt(10)
	v_mov_b32_e32 v115, v65
	v_mov_b32_e32 v108, v83
	v_mov_b32_e32 v109, v63
	s_waitcnt lgkmcnt(0)
	v_pk_add_f32 v[102:103], v[102:103], v[104:105]
	ds_bpermute_b32 v105, v99, v103
	ds_bpermute_b32 v104, v99, v102
	v_pk_fma_f32 v[106:107], v[106:107], v[106:107], v[110:111]
	v_mov_b32_e32 v112, v76
	v_mov_b32_e32 v113, v64
	v_pk_mul_f32 v[114:115], v[114:115], v[114:115]
	s_waitcnt lgkmcnt(0)
	v_pk_add_f32 v[102:103], v[102:103], v[104:105]
	ds_bpermute_b32 v105, v100, v103
	ds_bpermute_b32 v104, v100, v102
	v_pk_fma_f32 v[106:107], v[108:109], v[108:109], v[106:107]
	v_mov_b32_e32 v108, v78
	v_mov_b32_e32 v109, v66
	v_pk_fma_f32 v[112:113], v[112:113], v[112:113], v[114:115]
	s_waitcnt lgkmcnt(0)
	v_pk_add_f32 v[102:103], v[102:103], v[104:105]
	ds_bpermute_b32 v105, v101, v103
	ds_bpermute_b32 v104, v101, v102
	s_waitcnt vmcnt(8)
	v_mov_b32_e32 v114, v49
	s_waitcnt vmcnt(7)
	v_mov_b32_e32 v115, v53
	v_pk_fma_f32 v[108:109], v[108:109], v[108:109], v[112:113]
	v_mov_b32_e32 v112, v48
	v_mov_b32_e32 v113, v52
	v_pk_mul_f32 v[114:115], v[114:115], v[114:115]
	v_mov_b32_e32 v110, v79
	v_mov_b32_e32 v111, v67
	s_waitcnt lgkmcnt(0)
	v_pk_add_f32 v[102:103], v[102:103], v[104:105]
	v_mov_b32_e32 v104, v50
	v_mov_b32_e32 v105, v54
	v_pk_fma_f32 v[112:113], v[112:113], v[112:113], v[114:115]
	v_mov_b32_e32 v116, v45
	s_waitcnt vmcnt(6)
	v_mov_b32_e32 v117, v57
	v_pk_fma_f32 v[108:109], v[110:111], v[110:111], v[108:109]
	v_mov_b32_e32 v110, v51
	v_mov_b32_e32 v111, v55
	v_pk_fma_f32 v[104:105], v[104:105], v[104:105], v[112:113]
	v_mov_b32_e32 v114, v44
	v_mov_b32_e32 v115, v56
	v_pk_mul_f32 v[116:117], v[116:117], v[116:117]
	v_pk_fma_f32 v[104:105], v[110:111], v[110:111], v[104:105]
	v_mov_b32_e32 v110, v46
	v_mov_b32_e32 v111, v58
	v_pk_fma_f32 v[114:115], v[114:115], v[114:115], v[116:117]
	v_mov_b32_e32 v112, v47
	v_mov_b32_e32 v113, v59
	v_pk_fma_f32 v[110:111], v[110:111], v[110:111], v[114:115]
	v_pk_fma_f32 v[102:103], v[102:103], s[30:31], v[92:93] op_sel_hi:[1,0,0]
	v_pk_fma_f32 v[110:111], v[112:113], v[112:113], v[110:111]
	v_mov_b32_e32 v112, v108
	v_mov_b32_e32 v113, v106
	v_mov_b32_e32 v106, v109
	v_pk_add_f32 v[106:107], v[112:113], v[106:107]
	v_mov_b32_e32 v108, v110
	v_mov_b32_e32 v109, v104
	v_pk_add_f32 v[106:107], v[106:107], v[108:109]
	v_mov_b32_e32 v104, v111
	v_pk_add_f32 v[104:105], v[106:107], v[104:105]
	ds_bpermute_b32 v107, v96, v105
	ds_bpermute_b32 v106, v96, v104
	v_mul_f32_e32 v108, 0x4b800000, v103
	v_cmp_gt_f32_e32 vcc, s35, v103
	v_pk_add_f32 v[84:85], v[84:85], 1.0 op_sel_hi:[1,0]
	v_pk_add_f32 v[86:87], v[86:87], 1.0 op_sel_hi:[1,0]
	s_waitcnt lgkmcnt(0)
	v_pk_add_f32 v[104:105], v[104:105], v[106:107]
	ds_bpermute_b32 v107, v97, v105
	ds_bpermute_b32 v106, v97, v104
	v_cndmask_b32_e32 v103, v103, v108, vcc
	v_rsq_f32_e32 v103, v103
	v_pk_mul_f32 v[84:85], v[0:1], v[84:85]
	v_pk_mul_f32 v[86:87], v[2:3], v[86:87]
	s_waitcnt lgkmcnt(0)
	v_pk_add_f32 v[104:105], v[104:105], v[106:107]
	ds_bpermute_b32 v107, v98, v105
	ds_bpermute_b32 v106, v98, v104
	v_mul_f32_e32 v110, 0x45800000, v103
	v_cndmask_b32_e32 v110, v103, v110, vcc
	v_pk_mul_f32 v[32:33], v[32:33], v[110:111] op_sel_hi:[1,0]
	v_cmp_gt_f32_e32 vcc, s35, v102
	s_waitcnt lgkmcnt(0)
	v_pk_add_f32 v[104:105], v[104:105], v[106:107]
	ds_bpermute_b32 v107, v99, v105
	ds_bpermute_b32 v106, v99, v104
	v_pk_fma_f32 v[32:33], v[32:33], v[84:85], v[72:73]
	v_lshl_add_u64 v[108:109], s[58:59], 0, v[90:91]
	v_cvt_pk_bf16_f32 v32, v32, v33
	v_mul_f32_e32 v33, 0x4b800000, v102
	v_cndmask_b32_e32 v33, v102, v33, vcc
	v_rsq_f32_e32 v111, v33
	s_waitcnt lgkmcnt(0)
	v_pk_add_f32 v[102:103], v[104:105], v[106:107]
	ds_bpermute_b32 v105, v100, v103
	ds_bpermute_b32 v104, v100, v102
	v_pk_mul_f32 v[34:35], v[34:35], v[110:111] op_sel_hi:[1,0]
	v_mul_f32_e32 v106, 0x45800000, v111
	v_pk_fma_f32 v[34:35], v[34:35], v[86:87], v[74:75]
	v_pk_mul_f32 v[24:25], v[24:25], v[110:111] op_sel_hi:[1,0]
	v_cvt_pk_bf16_f32 v33, v34, v35
	s_waitcnt lgkmcnt(0)
	v_pk_add_f32 v[34:35], v[102:103], v[104:105]
	ds_bpermute_b32 v103, v101, v35
	ds_bpermute_b32 v102, v101, v34
	v_cndmask_b32_e32 v104, v111, v106, vcc
	v_pk_mul_f32 v[68:69], v[68:69], v[104:105] op_sel_hi:[1,0]
	v_pk_mul_f32 v[70:71], v[70:71], v[104:105] op_sel_hi:[1,0]
	v_pk_fma_f32 v[68:69], v[84:85], v[68:69], v[72:73]
	s_waitcnt lgkmcnt(0)
	v_pk_add_f32 v[34:35], v[34:35], v[102:103]
	v_cvt_pk_bf16_f32 v68, v68, v69
	v_pk_fma_f32 v[34:35], v[34:35], s[30:31], v[92:93] op_sel_hi:[1,0,0]
	v_pk_fma_f32 v[70:71], v[70:71], v[86:87], v[74:75]
	v_mul_f32_e32 v69, 0x4b800000, v35
	v_cmp_gt_f32_e32 vcc, s35, v35
	v_pk_mul_f32 v[26:27], v[26:27], v[110:111] op_sel_hi:[1,0]
	v_pk_mul_f32 v[40:41], v[40:41], v[104:105] op_sel_hi:[1,0]
	v_cndmask_b32_e32 v35, v35, v69, vcc
	v_rsq_f32_e32 v35, v35
	v_cvt_pk_bf16_f32 v69, v70, v71
	global_store_dwordx2 v90, v[32:33], s[58:59]
	global_store_dwordx2 v90, v[68:69], s[58:59] offset:2048
	v_pk_mul_f32 v[42:43], v[42:43], v[104:105] op_sel_hi:[1,0]
	v_mul_f32_e32 v70, 0x45800000, v35
	v_cndmask_b32_e32 v102, v35, v70, vcc
	v_mul_f32_e32 v35, 0x4b800000, v34
	v_cmp_gt_f32_e32 vcc, s35, v34
	v_pk_mul_f32 v[70:71], v[80:81], v[102:103] op_sel_hi:[1,0]
	v_pk_mul_f32 v[60:61], v[60:61], v[102:103] op_sel_hi:[1,0]
	v_cndmask_b32_e32 v34, v34, v35, vcc
	v_rsq_f32_e32 v80, v34
	v_pk_mul_f32 v[34:35], v[82:83], v[102:103] op_sel_hi:[1,0]
	v_pk_fma_f32 v[70:71], v[84:85], v[70:71], v[72:73]
	v_pk_fma_f32 v[34:35], v[86:87], v[34:35], v[74:75]
	v_cvt_pk_bf16_f32 v70, v70, v71
	v_cvt_pk_bf16_f32 v71, v34, v35
	v_mul_f32_e32 v34, 0x45800000, v80
	v_cndmask_b32_e32 v80, v80, v34, vcc
	v_pk_mul_f32 v[34:35], v[76:77], v[80:81] op_sel_hi:[1,0]
	v_add_co_u32_e32 v32, vcc, s31, v108
	v_pk_fma_f32 v[34:35], v[84:85], v[34:35], v[72:73]
	v_pk_mul_f32 v[72:73], v[78:79], v[80:81] op_sel_hi:[1,0]
	v_addc_co_u32_e32 v33, vcc, 0, v109, vcc
	v_pk_fma_f32 v[72:73], v[86:87], v[72:73], v[74:75]
	v_cvt_pk_bf16_f32 v34, v34, v35
	v_cvt_pk_bf16_f32 v35, v72, v73
	global_store_dwordx2 v[32:33], v[70:71], off
	global_store_dwordx2 v[32:33], v[34:35], off offset:2048
	s_nop 0
	v_pk_mul_f32 v[62:63], v[62:63], v[102:103] op_sel_hi:[1,0]
	v_lshl_add_u64 v[72:73], v[108:109], 0, s[4:5]
	v_pk_mul_f32 v[64:65], v[64:65], v[80:81] op_sel_hi:[1,0]
	v_pk_mul_f32 v[66:67], v[66:67], v[80:81] op_sel_hi:[1,0]
	v_lshl_add_u64 v[74:75], v[108:109], 0, s[12:13]
	v_pk_mul_f32 v[28:29], v[28:29], v[110:111] op_sel_hi:[1,0]
	v_pk_mul_f32 v[30:31], v[30:31], v[110:111] op_sel_hi:[1,0]
	v_pk_mul_f32 v[36:37], v[36:37], v[104:105] op_sel_hi:[1,0]
	v_pk_mul_f32 v[38:39], v[38:39], v[104:105] op_sel_hi:[1,0]
	v_pk_mul_f32 v[44:45], v[44:45], v[80:81] op_sel_hi:[1,0]
	v_pk_mul_f32 v[46:47], v[46:47], v[80:81] op_sel_hi:[1,0]
	v_pk_mul_f32 v[16:17], v[16:17], v[110:111] op_sel_hi:[1,0]
	v_pk_mul_f32 v[18:19], v[18:19], v[110:111] op_sel_hi:[1,0]
	v_pk_mul_f32 v[20:21], v[20:21], v[104:105] op_sel_hi:[1,0]
	v_pk_mul_f32 v[22:23], v[22:23], v[104:105] op_sel_hi:[1,0]
	s_waitcnt vmcnt(9)
	v_pk_add_f32 v[130:131], v[130:131], 1.0 op_sel_hi:[1,0]
	v_pk_add_f32 v[132:133], v[132:133], 1.0 op_sel_hi:[1,0]
	v_pk_mul_f32 v[130:131], v[4:5], v[130:131]
	v_pk_mul_f32 v[132:133], v[6:7], v[132:133]
	s_waitcnt vmcnt(8)
	v_pk_fma_f32 v[24:25], v[24:25], v[130:131], v[134:135]
	v_pk_fma_f32 v[26:27], v[26:27], v[132:133], v[136:137]
	v_cvt_pk_bf16_f32 v24, v24, v25
	v_cvt_pk_bf16_f32 v25, v26, v27
	global_store_dwordx2 v90, v[24:25], s[58:59] offset:512
	v_pk_fma_f32 v[24:25], v[40:41], v[130:131], v[134:135]
	v_pk_fma_f32 v[26:27], v[42:43], v[132:133], v[136:137]
	v_cvt_pk_bf16_f32 v24, v24, v25
	v_cvt_pk_bf16_f32 v25, v26, v27
	global_store_dwordx2 v90, v[24:25], s[58:59] offset:2560
	v_pk_fma_f32 v[24:25], v[60:61], v[130:131], v[134:135]
	v_pk_fma_f32 v[26:27], v[62:63], v[132:133], v[136:137]
	v_cvt_pk_bf16_f32 v24, v24, v25
	v_cvt_pk_bf16_f32 v25, v26, v27
	global_store_dwordx2 v[72:73], v[24:25], off offset:512
	v_pk_fma_f32 v[24:25], v[64:65], v[130:131], v[134:135]
	v_pk_fma_f32 v[26:27], v[66:67], v[132:133], v[136:137]
	v_cvt_pk_bf16_f32 v24, v24, v25
	v_cvt_pk_bf16_f32 v25, v26, v27
	global_store_dwordx2 v[74:75], v[24:25], off offset:512
	s_nop 0
	v_pk_mul_f32 v[40:41], v[48:49], v[102:103] op_sel_hi:[1,0]
	v_pk_mul_f32 v[42:43], v[50:51], v[102:103] op_sel_hi:[1,0]
	s_waitcnt vmcnt(11)
	v_pk_add_f32 v[138:139], v[138:139], 1.0 op_sel_hi:[1,0]
	v_pk_add_f32 v[140:141], v[140:141], 1.0 op_sel_hi:[1,0]
	v_pk_mul_f32 v[138:139], v[8:9], v[138:139]
	v_pk_mul_f32 v[140:141], v[10:11], v[140:141]
	s_waitcnt vmcnt(10)
	v_pk_fma_f32 v[28:29], v[28:29], v[138:139], v[142:143]
	v_pk_fma_f32 v[30:31], v[30:31], v[140:141], v[144:145]
	v_cvt_pk_bf16_f32 v28, v28, v29
	v_cvt_pk_bf16_f32 v29, v30, v31
	global_store_dwordx2 v90, v[28:29], s[58:59] offset:1024
	v_pk_fma_f32 v[28:29], v[36:37], v[138:139], v[142:143]
	v_pk_fma_f32 v[30:31], v[38:39], v[140:141], v[144:145]
	v_cvt_pk_bf16_f32 v28, v28, v29
	v_cvt_pk_bf16_f32 v29, v30, v31
	global_store_dwordx2 v90, v[28:29], s[58:59] offset:3072
	v_pk_fma_f32 v[28:29], v[40:41], v[138:139], v[142:143]
	v_pk_fma_f32 v[30:31], v[42:43], v[140:141], v[144:145]
	v_pk_fma_f32 v[138:139], v[44:45], v[138:139], v[142:143]
	v_pk_fma_f32 v[140:141], v[46:47], v[140:141], v[144:145]
	v_cvt_pk_bf16_f32 v28, v28, v29
	v_cvt_pk_bf16_f32 v29, v30, v31
	v_cvt_pk_bf16_f32 v138, v138, v139
	v_cvt_pk_bf16_f32 v139, v140, v141
	global_store_dwordx2 v[72:73], v[28:29], off offset:1024
	global_store_dwordx2 v[74:75], v[138:139], off offset:1024
	s_nop 0
	v_pk_mul_f32 v[32:33], v[52:53], v[102:103] op_sel_hi:[1,0]
	v_pk_mul_f32 v[34:35], v[54:55], v[102:103] op_sel_hi:[1,0]
	v_pk_mul_f32 v[36:37], v[56:57], v[80:81] op_sel_hi:[1,0]
	v_pk_mul_f32 v[38:39], v[58:59], v[80:81] op_sel_hi:[1,0]
	s_waitcnt vmcnt(13)
	v_pk_add_f32 v[146:147], v[146:147], 1.0 op_sel_hi:[1,0]
	v_pk_add_f32 v[148:149], v[148:149], 1.0 op_sel_hi:[1,0]
	v_pk_mul_f32 v[146:147], v[12:13], v[146:147]
	v_pk_mul_f32 v[148:149], v[14:15], v[148:149]
	s_waitcnt vmcnt(12)
	v_pk_fma_f32 v[16:17], v[16:17], v[146:147], v[150:151]
	v_pk_fma_f32 v[18:19], v[18:19], v[148:149], v[152:153]
	v_pk_fma_f32 v[20:21], v[20:21], v[146:147], v[150:151]
	v_pk_fma_f32 v[22:23], v[22:23], v[148:149], v[152:153]
	v_pk_fma_f32 v[32:33], v[32:33], v[146:147], v[150:151]
	v_pk_fma_f32 v[34:35], v[34:35], v[148:149], v[152:153]
	v_pk_fma_f32 v[146:147], v[36:37], v[146:147], v[150:151]
	v_pk_fma_f32 v[148:149], v[38:39], v[148:149], v[152:153]
	v_cvt_pk_bf16_f32 v16, v16, v17
	v_cvt_pk_bf16_f32 v17, v18, v19
	v_cvt_pk_bf16_f32 v18, v20, v21
	v_cvt_pk_bf16_f32 v19, v22, v23
	v_cvt_pk_bf16_f32 v20, v32, v33
	v_cvt_pk_bf16_f32 v21, v34, v35
	v_cvt_pk_bf16_f32 v22, v146, v147
	v_cvt_pk_bf16_f32 v23, v148, v149
	global_store_dwordx2 v90, v[16:17], s[58:59] offset:1536
	global_store_dwordx2 v90, v[18:19], s[58:59] offset:3584
	global_store_dwordx2 v[72:73], v[20:21], off offset:1536
	global_store_dwordx2 v[74:75], v[22:23], off offset:1536
	s_cbranch_scc0 .LBB0_73

.LBB0_519:
	s_lshl_b64 s[38:39], s[52:53], s60
	s_add_u32 s1, s56, s38
	s_addc_u32 s2, s57, s39
	s_lshl_b64 s[38:39], s[58:59], 12
	s_add_u32 s52, s1, s38
	s_addc_u32 s53, s2, s39
	v_lshl_add_u64 v[40:41], s[52:53], 0, v[84:85]
	global_load_dwordx4 v[32:35], v84, s[52:53]
	global_load_dwordx4 v[24:27], v84, s[52:53] offset:1024
	v_add_co_u32_e32 v42, vcc, s35, v40
	global_load_dwordx4 v[28:31], v84, s[52:53] offset:2048
	s_nop 0
	v_addc_co_u32_e32 v43, vcc, 0, v41, vcc
	v_lshl_add_u64 v[20:21], v[40:41], 0, s[4:5]
	global_load_dwordx4 v[68:71], v[42:43], off offset:-4096
	global_load_dwordx4 v[44:47], v[20:21], off offset:1024
	global_load_dwordx4 v[16:19], v84, s[52:53] offset:3072
	global_load_dwordx4 v[36:39], v[20:21], off offset:2048
	s_nop 0
	global_load_dwordx4 v[20:23], v[20:21], off offset:3072
	s_add_u32 s30, s20, s30
	s_addc_u32 s31, s21, s31
	v_lshl_add_u64 v[52:53], v[40:41], 0, s[6:7]
	v_lshl_add_u64 v[90:91], s[30:31], 0, v[84:85]
	global_load_dwordx4 v[56:59], v[52:53], off offset:1024
	global_load_dwordx4 v[76:79], v[42:43], off
	v_add_co_u32_e32 v48, vcc, s25, v90
	v_lshl_add_u64 v[60:61], v[40:41], 0, s[8:9]
	s_nop 0
	v_addc_co_u32_e32 v49, vcc, 0, v91, vcc
	v_add_co_u32_e32 v40, vcc, s33, v40
	global_load_dwordx4 v[80:83], v[48:49], off
	s_nop 0
	v_addc_co_u32_e32 v41, vcc, 0, v41, vcc
	global_load_dwordx4 v[72:75], v[40:41], off
	global_load_dwordx4 v[64:67], v[60:61], off offset:1024
	s_nop 0
	global_load_dwordx4 v[40:43], v[60:61], off offset:2048
	global_load_dwordx4 v[48:51], v[52:53], off offset:2048
	s_nop 0
	global_load_dwordx4 v[52:55], v[52:53], off offset:3072
	s_nop 0
	global_load_dwordx4 v[60:63], v[60:61], off offset:3072
	v_add_co_u32_e32 v100, vcc, s33, v90
	s_ashr_i32 s1, s0, 31
	s_nop 0
	v_addc_co_u32_e32 v101, vcc, 0, v91, vcc
	global_load_dwordx4 v[100:103], v[100:101], off
	s_lshl_b64 s[30:31], s[0:1], 11
	v_readlane_b32 s40, v239, 32
	v_readlane_b32 s41, v239, 33
	s_add_u32 s30, s40, s30
	s_addc_u32 s31, s41, s31
	v_lshl_add_u64 v[92:93], v[90:91], 0, s[12:13]
	s_add_i32 s0, s0, s11
	s_cmp_lt_i32 s0, 0x9000
	v_readlane_b32 s42, v239, 34
	v_readlane_b32 s43, v239, 35
	v_readlane_b32 s44, v239, 36
	v_readlane_b32 s45, v239, 37
	v_readlane_b32 s46, v239, 38
	v_readlane_b32 s47, v239, 39
	global_load_dwordx4 v[128:131], v[92:93], off offset:1024
	v_lshl_add_u64 v[132:133], v[90:91], 0, s[8:9]
	global_load_dwordx4 v[134:137], v[132:133], off offset:1024
	global_load_dwordx4 v[138:141], v[92:93], off offset:2048
	global_load_dwordx4 v[142:145], v[132:133], off offset:2048
	global_load_dwordx4 v[146:149], v[92:93], off offset:3072
	global_load_dwordx4 v[150:153], v[132:133], off offset:3072
	s_waitcnt vmcnt(23)
	v_mov_b32_e32 v110, v33
	s_waitcnt vmcnt(22)
	v_mov_b32_e32 v111, v25
	v_mov_b32_e32 v108, v32
	v_mov_b32_e32 v109, v24
	v_pk_mul_f32 v[110:111], v[110:111], v[110:111]
	v_mov_b32_e32 v104, v34
	v_mov_b32_e32 v105, v26
	s_waitcnt vmcnt(21)
	v_mov_b32_e32 v118, v29
	v_pk_fma_f32 v[108:109], v[108:109], v[108:109], v[110:111]
	s_waitcnt vmcnt(20)
	v_mov_b32_e32 v124, v69
	s_waitcnt vmcnt(19)
	v_mov_b32_e32 v125, v45
	s_waitcnt vmcnt(18)
	v_mov_b32_e32 v119, v17
	v_mov_b32_e32 v106, v35
	v_mov_b32_e32 v107, v27
	v_mov_b32_e32 v116, v28
	v_mov_b32_e32 v122, v68
	v_mov_b32_e32 v123, v44
	v_mov_b32_e32 v117, v16
	v_pk_fma_f32 v[104:105], v[104:105], v[104:105], v[108:109]
	v_pk_mul_f32 v[108:109], v[124:125], v[124:125]
	v_pk_mul_f32 v[118:119], v[118:119], v[118:119]
	v_mov_b32_e32 v112, v30
	v_mov_b32_e32 v113, v18
	v_pk_fma_f32 v[104:105], v[106:107], v[106:107], v[104:105]
	v_pk_fma_f32 v[106:107], v[122:123], v[122:123], v[108:109]
	v_pk_fma_f32 v[108:109], v[116:117], v[116:117], v[118:119]
	v_mov_b32_e32 v114, v31
	v_mov_b32_e32 v115, v19
	v_pk_fma_f32 v[108:109], v[112:113], v[112:113], v[108:109]
	v_mov_b32_e32 v110, v70
	v_pk_fma_f32 v[108:109], v[114:115], v[114:115], v[108:109]
	s_waitcnt vmcnt(17)
	v_mov_b32_e32 v114, v37
	s_waitcnt vmcnt(16)
	v_mov_b32_e32 v115, v21
	v_mov_b32_e32 v111, v46
	v_mov_b32_e32 v112, v36
	v_mov_b32_e32 v113, v20
	v_pk_mul_f32 v[114:115], v[114:115], v[114:115]
	v_mov_b32_e32 v120, v71
	v_mov_b32_e32 v121, v47
	v_mov_b32_e32 v126, v38
	v_mov_b32_e32 v127, v22
	v_pk_fma_f32 v[106:107], v[110:111], v[110:111], v[106:107]
	v_pk_fma_f32 v[112:113], v[112:113], v[112:113], v[114:115]
	v_pk_fma_f32 v[106:107], v[120:121], v[120:121], v[106:107]
	v_mov_b32_e32 v110, v39
	v_mov_b32_e32 v111, v23
	v_pk_fma_f32 v[112:113], v[126:127], v[126:127], v[112:113]
	s_waitcnt vmcnt(14)
	v_mov_b32_e32 v114, v77
	v_pk_fma_f32 v[110:111], v[110:111], v[110:111], v[112:113]
	v_mov_b32_e32 v112, v106
	v_mov_b32_e32 v113, v104
	v_mov_b32_e32 v104, v107
	v_pk_add_f32 v[104:105], v[112:113], v[104:105]
	v_mov_b32_e32 v106, v110
	v_mov_b32_e32 v107, v108
	v_pk_add_f32 v[104:105], v[104:105], v[106:107]
	v_mov_b32_e32 v108, v111
	v_pk_add_f32 v[104:105], v[104:105], v[108:109]
	ds_bpermute_b32 v107, v94, v105
	ds_bpermute_b32 v106, v94, v104
	v_mov_b32_e32 v115, v57
	v_mov_b32_e32 v112, v76
	v_mov_b32_e32 v113, v56
	v_pk_mul_f32 v[114:115], v[114:115], v[114:115]
	s_waitcnt lgkmcnt(0)
	v_pk_add_f32 v[104:105], v[104:105], v[106:107]
	ds_bpermute_b32 v107, v95, v105
	ds_bpermute_b32 v106, v95, v104
	v_mov_b32_e32 v108, v78
	v_mov_b32_e32 v109, v58
	v_pk_fma_f32 v[112:113], v[112:113], v[112:113], v[114:115]
	s_waitcnt vmcnt(12)
	v_mov_b32_e32 v116, v73
	s_waitcnt lgkmcnt(0)
	v_pk_add_f32 v[104:105], v[104:105], v[106:107]
	ds_bpermute_b32 v107, v96, v105
	ds_bpermute_b32 v106, v96, v104
	s_waitcnt vmcnt(11)
	v_mov_b32_e32 v117, v65
	v_mov_b32_e32 v110, v79
	v_mov_b32_e32 v111, v59
	v_pk_fma_f32 v[108:109], v[108:109], v[108:109], v[112:113]
	s_waitcnt lgkmcnt(0)
	v_pk_add_f32 v[104:105], v[104:105], v[106:107]
	ds_bpermute_b32 v107, v97, v105
	ds_bpermute_b32 v106, v97, v104
	v_mov_b32_e32 v114, v72
	v_mov_b32_e32 v115, v64
	v_pk_mul_f32 v[116:117], v[116:117], v[116:117]
	v_pk_fma_f32 v[108:109], v[110:111], v[110:111], v[108:109]
	s_waitcnt lgkmcnt(0)
	v_pk_add_f32 v[104:105], v[104:105], v[106:107]
	ds_bpermute_b32 v107, v98, v105
	ds_bpermute_b32 v106, v98, v104
	v_mov_b32_e32 v110, v74
	v_mov_b32_e32 v111, v66
	v_pk_fma_f32 v[114:115], v[114:115], v[114:115], v[116:117]
	s_waitcnt vmcnt(9)
	v_mov_b32_e32 v116, v49
	s_waitcnt lgkmcnt(0)
	v_pk_add_f32 v[104:105], v[104:105], v[106:107]
	ds_bpermute_b32 v107, v99, v105
	ds_bpermute_b32 v106, v99, v104
	s_waitcnt vmcnt(8)
	v_mov_b32_e32 v117, v53
	v_pk_fma_f32 v[110:111], v[110:111], v[110:111], v[114:115]
	v_mov_b32_e32 v114, v48
	v_mov_b32_e32 v115, v52
	v_pk_mul_f32 v[116:117], v[116:117], v[116:117]
	v_mov_b32_e32 v112, v75
	v_mov_b32_e32 v113, v67
	s_waitcnt lgkmcnt(0)
	v_pk_add_f32 v[104:105], v[104:105], v[106:107]
	v_mov_b32_e32 v106, v50
	v_mov_b32_e32 v107, v54
	v_pk_fma_f32 v[114:115], v[114:115], v[114:115], v[116:117]
	v_mov_b32_e32 v118, v41
	s_waitcnt vmcnt(7)
	v_mov_b32_e32 v119, v61
	v_pk_fma_f32 v[110:111], v[112:113], v[112:113], v[110:111]
	v_mov_b32_e32 v112, v51
	v_mov_b32_e32 v113, v55
	v_pk_fma_f32 v[106:107], v[106:107], v[106:107], v[114:115]
	v_mov_b32_e32 v116, v40
	v_mov_b32_e32 v117, v60
	v_pk_mul_f32 v[118:119], v[118:119], v[118:119]
	v_pk_fma_f32 v[106:107], v[112:113], v[112:113], v[106:107]
	v_mov_b32_e32 v112, v42
	v_mov_b32_e32 v113, v62
	v_pk_fma_f32 v[116:117], v[116:117], v[116:117], v[118:119]
	v_mov_b32_e32 v114, v43
	v_mov_b32_e32 v115, v63
	v_pk_fma_f32 v[112:113], v[112:113], v[112:113], v[116:117]
	v_pk_fma_f32 v[104:105], v[104:105], s[24:25], v[88:89] op_sel_hi:[1,0,0]
	v_pk_fma_f32 v[112:113], v[114:115], v[114:115], v[112:113]
	v_mov_b32_e32 v114, v110
	v_mov_b32_e32 v115, v108
	v_mov_b32_e32 v108, v111
	v_pk_add_f32 v[108:109], v[114:115], v[108:109]
	v_mov_b32_e32 v110, v112
	v_mov_b32_e32 v111, v106
	v_pk_add_f32 v[108:109], v[108:109], v[110:111]
	v_mov_b32_e32 v106, v113
	v_pk_add_f32 v[106:107], v[108:109], v[106:107]
	ds_bpermute_b32 v109, v94, v107
	ds_bpermute_b32 v108, v94, v106
	v_mul_f32_e32 v110, 0x4b800000, v105
	v_cmp_gt_f32_e32 vcc, s36, v105
	v_pk_add_f32 v[80:81], v[80:81], 1.0 op_sel_hi:[1,0]
	v_pk_add_f32 v[82:83], v[82:83], 1.0 op_sel_hi:[1,0]
	s_waitcnt lgkmcnt(0)
	v_pk_add_f32 v[106:107], v[106:107], v[108:109]
	ds_bpermute_b32 v109, v95, v107
	ds_bpermute_b32 v108, v95, v106
	v_cndmask_b32_e32 v105, v105, v110, vcc
	v_rsq_f32_e32 v105, v105
	v_pk_mul_f32 v[80:81], v[0:1], v[80:81]
	v_pk_mul_f32 v[82:83], v[2:3], v[82:83]
	s_waitcnt lgkmcnt(0)
	v_pk_add_f32 v[106:107], v[106:107], v[108:109]
	ds_bpermute_b32 v109, v96, v107
	ds_bpermute_b32 v108, v96, v106
	v_mul_f32_e32 v112, 0x45800000, v105
	v_cndmask_b32_e32 v112, v105, v112, vcc
	v_pk_mul_f32 v[32:33], v[32:33], v[112:113] op_sel_hi:[1,0]
	v_cmp_gt_f32_e32 vcc, s36, v104
	s_waitcnt lgkmcnt(0)
	v_pk_add_f32 v[106:107], v[106:107], v[108:109]
	ds_bpermute_b32 v109, v97, v107
	ds_bpermute_b32 v108, v97, v106
	s_waitcnt vmcnt(6)
	v_pk_fma_f32 v[32:33], v[32:33], v[80:81], v[100:101]
	v_lshl_add_u64 v[110:111], s[30:31], 0, v[86:87]
	v_cvt_pk_bf16_f32 v32, v32, v33
	v_mul_f32_e32 v33, 0x4b800000, v104
	v_cndmask_b32_e32 v33, v104, v33, vcc
	v_rsq_f32_e32 v113, v33
	s_waitcnt lgkmcnt(0)
	v_pk_add_f32 v[104:105], v[106:107], v[108:109]
	ds_bpermute_b32 v107, v98, v105
	ds_bpermute_b32 v106, v98, v104
	v_pk_mul_f32 v[34:35], v[34:35], v[112:113] op_sel_hi:[1,0]
	v_mul_f32_e32 v108, 0x45800000, v113
	v_pk_fma_f32 v[34:35], v[34:35], v[82:83], v[102:103]
	v_pk_mul_f32 v[24:25], v[24:25], v[112:113] op_sel_hi:[1,0]
	v_cvt_pk_bf16_f32 v33, v34, v35
	s_waitcnt lgkmcnt(0)
	v_pk_add_f32 v[34:35], v[104:105], v[106:107]
	ds_bpermute_b32 v105, v99, v35
	ds_bpermute_b32 v104, v99, v34
	v_cndmask_b32_e32 v106, v113, v108, vcc
	v_pk_mul_f32 v[68:69], v[68:69], v[106:107] op_sel_hi:[1,0]
	v_pk_mul_f32 v[70:71], v[70:71], v[106:107] op_sel_hi:[1,0]
	v_pk_fma_f32 v[68:69], v[80:81], v[68:69], v[100:101]
	s_waitcnt lgkmcnt(0)
	v_pk_add_f32 v[34:35], v[34:35], v[104:105]
	v_cvt_pk_bf16_f32 v68, v68, v69
	v_pk_fma_f32 v[34:35], v[34:35], s[24:25], v[88:89] op_sel_hi:[1,0,0]
	v_pk_fma_f32 v[70:71], v[70:71], v[82:83], v[102:103]
	v_mul_f32_e32 v69, 0x4b800000, v35
	v_cmp_gt_f32_e32 vcc, s36, v35
	v_pk_mul_f32 v[26:27], v[26:27], v[112:113] op_sel_hi:[1,0]
	v_pk_mul_f32 v[44:45], v[44:45], v[106:107] op_sel_hi:[1,0]
	v_cndmask_b32_e32 v35, v35, v69, vcc
	v_rsq_f32_e32 v35, v35
	v_cvt_pk_bf16_f32 v69, v70, v71
	global_store_dwordx2 v86, v[32:33], s[30:31]
	global_store_dwordx2 v86, v[68:69], s[30:31] offset:2048
	v_pk_mul_f32 v[46:47], v[46:47], v[106:107] op_sel_hi:[1,0]
	v_mul_f32_e32 v70, 0x45800000, v35
	v_cndmask_b32_e32 v104, v35, v70, vcc
	v_mul_f32_e32 v35, 0x4b800000, v34
	v_cmp_gt_f32_e32 vcc, s36, v34
	v_pk_mul_f32 v[70:71], v[76:77], v[104:105] op_sel_hi:[1,0]
	v_pk_mul_f32 v[56:57], v[56:57], v[104:105] op_sel_hi:[1,0]
	v_cndmask_b32_e32 v34, v34, v35, vcc
	v_rsq_f32_e32 v76, v34
	v_pk_mul_f32 v[34:35], v[78:79], v[104:105] op_sel_hi:[1,0]
	v_pk_fma_f32 v[70:71], v[80:81], v[70:71], v[100:101]
	v_pk_fma_f32 v[34:35], v[82:83], v[34:35], v[102:103]
	v_cvt_pk_bf16_f32 v70, v70, v71
	v_cvt_pk_bf16_f32 v71, v34, v35
	v_mul_f32_e32 v34, 0x45800000, v76
	v_cndmask_b32_e32 v76, v76, v34, vcc
	v_pk_mul_f32 v[34:35], v[72:73], v[76:77] op_sel_hi:[1,0]
	v_pk_mul_f32 v[72:73], v[74:75], v[76:77] op_sel_hi:[1,0]
	v_add_co_u32_e32 v32, vcc, s34, v110
	v_pk_fma_f32 v[34:35], v[80:81], v[34:35], v[100:101]
	v_pk_fma_f32 v[72:73], v[82:83], v[72:73], v[102:103]
	v_addc_co_u32_e32 v33, vcc, 0, v111, vcc
	v_cvt_pk_bf16_f32 v34, v34, v35
	v_cvt_pk_bf16_f32 v35, v72, v73
	global_store_dwordx2 v[32:33], v[70:71], off
	global_store_dwordx2 v[32:33], v[34:35], off offset:2048
	v_lshl_add_u64 v[72:73], v[90:91], 0, s[8:9]
	v_pk_mul_f32 v[58:59], v[58:59], v[104:105] op_sel_hi:[1,0]
	v_lshl_add_u64 v[74:75], v[110:111], 0, s[4:5]
	v_pk_mul_f32 v[64:65], v[64:65], v[76:77] op_sel_hi:[1,0]
	v_pk_mul_f32 v[66:67], v[66:67], v[76:77] op_sel_hi:[1,0]
	v_lshl_add_u64 v[78:79], v[110:111], 0, s[22:23]
	v_pk_mul_f32 v[28:29], v[28:29], v[112:113] op_sel_hi:[1,0]
	v_pk_mul_f32 v[30:31], v[30:31], v[112:113] op_sel_hi:[1,0]
	v_pk_mul_f32 v[36:37], v[36:37], v[106:107] op_sel_hi:[1,0]
	v_pk_mul_f32 v[38:39], v[38:39], v[106:107] op_sel_hi:[1,0]
	v_pk_mul_f32 v[40:41], v[40:41], v[76:77] op_sel_hi:[1,0]
	v_pk_mul_f32 v[42:43], v[42:43], v[76:77] op_sel_hi:[1,0]
	v_pk_mul_f32 v[16:17], v[16:17], v[112:113] op_sel_hi:[1,0]
	v_pk_mul_f32 v[18:19], v[18:19], v[112:113] op_sel_hi:[1,0]
	v_pk_mul_f32 v[20:21], v[20:21], v[106:107] op_sel_hi:[1,0]
	v_pk_mul_f32 v[22:23], v[22:23], v[106:107] op_sel_hi:[1,0]
	s_waitcnt vmcnt(9)
	v_pk_add_f32 v[128:129], v[128:129], 1.0 op_sel_hi:[1,0]
	v_pk_add_f32 v[130:131], v[130:131], 1.0 op_sel_hi:[1,0]
	v_pk_mul_f32 v[128:129], v[4:5], v[128:129]
	v_pk_mul_f32 v[130:131], v[6:7], v[130:131]
	s_waitcnt vmcnt(8)
	v_pk_fma_f32 v[24:25], v[24:25], v[128:129], v[134:135]
	v_pk_fma_f32 v[26:27], v[26:27], v[130:131], v[136:137]
	v_cvt_pk_bf16_f32 v24, v24, v25
	v_cvt_pk_bf16_f32 v25, v26, v27
	global_store_dwordx2 v86, v[24:25], s[30:31] offset:512
	v_pk_fma_f32 v[24:25], v[44:45], v[128:129], v[134:135]
	v_pk_fma_f32 v[26:27], v[46:47], v[130:131], v[136:137]
	v_cvt_pk_bf16_f32 v24, v24, v25
	v_cvt_pk_bf16_f32 v25, v26, v27
	global_store_dwordx2 v86, v[24:25], s[30:31] offset:2560
	v_pk_fma_f32 v[24:25], v[56:57], v[128:129], v[134:135]
	v_pk_fma_f32 v[26:27], v[58:59], v[130:131], v[136:137]
	v_cvt_pk_bf16_f32 v24, v24, v25
	v_cvt_pk_bf16_f32 v25, v26, v27
	global_store_dwordx2 v[74:75], v[24:25], off offset:512
	v_pk_fma_f32 v[24:25], v[64:65], v[128:129], v[134:135]
	v_pk_fma_f32 v[26:27], v[66:67], v[130:131], v[136:137]
	v_cvt_pk_bf16_f32 v24, v24, v25
	v_cvt_pk_bf16_f32 v25, v26, v27
	global_store_dwordx2 v[78:79], v[24:25], off offset:512
	s_nop 0
	v_pk_mul_f32 v[44:45], v[48:49], v[104:105] op_sel_hi:[1,0]
	v_pk_mul_f32 v[46:47], v[50:51], v[104:105] op_sel_hi:[1,0]
	s_waitcnt vmcnt(11)
	v_pk_add_f32 v[138:139], v[138:139], 1.0 op_sel_hi:[1,0]
	v_pk_add_f32 v[140:141], v[140:141], 1.0 op_sel_hi:[1,0]
	v_pk_mul_f32 v[138:139], v[8:9], v[138:139]
	v_pk_mul_f32 v[140:141], v[10:11], v[140:141]
	s_waitcnt vmcnt(10)
	v_pk_fma_f32 v[28:29], v[28:29], v[138:139], v[142:143]
	v_pk_fma_f32 v[30:31], v[30:31], v[140:141], v[144:145]
	v_cvt_pk_bf16_f32 v28, v28, v29
	v_cvt_pk_bf16_f32 v29, v30, v31
	global_store_dwordx2 v86, v[28:29], s[30:31] offset:1024
	v_pk_fma_f32 v[28:29], v[36:37], v[138:139], v[142:143]
	v_pk_fma_f32 v[30:31], v[38:39], v[140:141], v[144:145]
	v_cvt_pk_bf16_f32 v28, v28, v29
	v_cvt_pk_bf16_f32 v29, v30, v31
	global_store_dwordx2 v86, v[28:29], s[30:31] offset:3072
	v_pk_fma_f32 v[28:29], v[44:45], v[138:139], v[142:143]
	v_pk_fma_f32 v[30:31], v[46:47], v[140:141], v[144:145]
	v_pk_fma_f32 v[138:139], v[40:41], v[138:139], v[142:143]
	v_pk_fma_f32 v[140:141], v[42:43], v[140:141], v[144:145]
	v_cvt_pk_bf16_f32 v28, v28, v29
	v_cvt_pk_bf16_f32 v29, v30, v31
	v_cvt_pk_bf16_f32 v138, v138, v139
	v_cvt_pk_bf16_f32 v139, v140, v141
	global_store_dwordx2 v[74:75], v[28:29], off offset:1024
	global_store_dwordx2 v[78:79], v[138:139], off offset:1024
	s_nop 0
	v_pk_mul_f32 v[32:33], v[52:53], v[104:105] op_sel_hi:[1,0]
	v_pk_mul_f32 v[34:35], v[54:55], v[104:105] op_sel_hi:[1,0]
	v_pk_mul_f32 v[36:37], v[60:61], v[76:77] op_sel_hi:[1,0]
	v_pk_mul_f32 v[38:39], v[62:63], v[76:77] op_sel_hi:[1,0]
	s_waitcnt vmcnt(13)
	v_pk_add_f32 v[146:147], v[146:147], 1.0 op_sel_hi:[1,0]
	v_pk_add_f32 v[148:149], v[148:149], 1.0 op_sel_hi:[1,0]
	v_pk_mul_f32 v[146:147], v[12:13], v[146:147]
	v_pk_mul_f32 v[148:149], v[14:15], v[148:149]
	s_waitcnt vmcnt(12)
	v_pk_fma_f32 v[16:17], v[16:17], v[146:147], v[150:151]
	v_pk_fma_f32 v[18:19], v[18:19], v[148:149], v[152:153]
	v_pk_fma_f32 v[20:21], v[20:21], v[146:147], v[150:151]
	v_pk_fma_f32 v[22:23], v[22:23], v[148:149], v[152:153]
	v_pk_fma_f32 v[32:33], v[32:33], v[146:147], v[150:151]
	v_pk_fma_f32 v[34:35], v[34:35], v[148:149], v[152:153]
	v_pk_fma_f32 v[146:147], v[36:37], v[146:147], v[150:151]
	v_pk_fma_f32 v[148:149], v[38:39], v[148:149], v[152:153]
	v_cvt_pk_bf16_f32 v16, v16, v17
	v_cvt_pk_bf16_f32 v17, v18, v19
	v_cvt_pk_bf16_f32 v18, v20, v21
	v_cvt_pk_bf16_f32 v19, v22, v23
	v_cvt_pk_bf16_f32 v20, v32, v33
	v_cvt_pk_bf16_f32 v21, v34, v35
	v_cvt_pk_bf16_f32 v22, v146, v147
	v_cvt_pk_bf16_f32 v23, v148, v149
	global_store_dwordx2 v86, v[16:17], s[30:31] offset:1536
	global_store_dwordx2 v86, v[18:19], s[30:31] offset:3584
	global_store_dwordx2 v[74:75], v[20:21], off offset:1536
	global_store_dwordx2 v[78:79], v[22:23], off offset:1536
	s_cbranch_scc0 .LBB0_523

.LBB0_873:
	s_lshl_b64 s[30:31], s[30:31], s52
	s_add_u32 s1, s40, s30
	s_addc_u32 s4, s41, s31
	s_lshl_b64 s[30:31], s[42:43], 12
	s_add_u32 s30, s1, s30
	s_addc_u32 s31, s4, s31
	global_load_dwordx4 v[32:35], v88, s[30:31]
	global_load_dwordx4 v[24:27], v88, s[30:31] offset:1024
	v_lshl_add_u64 v[44:45], s[30:31], 0, v[88:89]
	v_add_co_u32_e32 v46, vcc, s33, v44
	v_lshl_add_u64 v[20:21], v[44:45], 0, s[2:3]
	s_nop 0
	v_addc_co_u32_e32 v47, vcc, 0, v45, vcc
	global_load_dwordx4 v[28:31], v88, s[30:31] offset:2048
	global_load_dwordx4 v[68:71], v[46:47], off offset:-4096
	global_load_dwordx4 v[40:43], v[20:21], off offset:1024
	global_load_dwordx4 v[16:19], v88, s[30:31] offset:3072
	global_load_dwordx4 v[36:39], v[20:21], off offset:2048
	s_nop 0
	global_load_dwordx4 v[20:23], v[20:21], off offset:3072
	s_add_u32 s24, s20, s24
	s_addc_u32 s25, s21, s25
	v_lshl_add_u64 v[94:95], s[24:25], 0, v[88:89]
	v_add_co_u32_e32 v48, vcc, s11, v94
	v_lshl_add_u64 v[52:53], v[44:45], 0, s[6:7]
	s_nop 0
	v_addc_co_u32_e32 v49, vcc, 0, v95, vcc
	global_load_dwordx4 v[84:87], v[48:49], off
	global_load_dwordx4 v[80:83], v[46:47], off
	global_load_dwordx4 v[60:63], v[52:53], off offset:1024
	global_load_dwordx4 v[72:75], v88, s[24:25]
	v_lshl_add_u64 v[56:57], v[44:45], 0, s[8:9]
	v_add_co_u32_e32 v44, vcc, s34, v44
	s_ashr_i32 s1, s0, 31
	s_nop 0
	v_addc_co_u32_e32 v45, vcc, 0, v45, vcc
	global_load_dwordx4 v[76:79], v[44:45], off
	global_load_dwordx4 v[64:67], v[56:57], off offset:1024
	s_nop 0
	global_load_dwordx4 v[44:47], v[56:57], off offset:2048
	global_load_dwordx4 v[48:51], v[52:53], off offset:2048
	s_nop 0
	global_load_dwordx4 v[52:55], v[52:53], off offset:3072
	s_nop 0
	global_load_dwordx4 v[56:59], v[56:57], off offset:3072
	s_lshl_b64 s[30:31], s[0:1], 11
	v_readlane_b32 s36, v239, 32
	v_readlane_b32 s37, v239, 33
	s_add_u32 s30, s36, s30
	s_addc_u32 s31, s37, s31
	v_lshl_add_u64 v[94:95], v[94:95], 0, s[2:3]
	s_add_i32 s0, s0, s23
	s_cmp_lt_i32 s0, 0x9000
	v_readlane_b32 s38, v239, 34
	v_readlane_b32 s39, v239, 35
	v_readlane_b32 s40, v239, 36
	v_readlane_b32 s41, v239, 37
	v_readlane_b32 s42, v239, 38
	v_readlane_b32 s43, v239, 39
	global_load_dwordx4 v[130:133], v[94:95], off offset:1024
	global_load_dwordx4 v[134:137], v88, s[24:25] offset:1024
	global_load_dwordx4 v[138:141], v[94:95], off offset:2048
	global_load_dwordx4 v[142:145], v88, s[24:25] offset:2048
	global_load_dwordx4 v[146:149], v[94:95], off offset:3072
	global_load_dwordx4 v[150:153], v88, s[24:25] offset:3072
	s_waitcnt vmcnt(23)
	v_mov_b32_e32 v108, v33
	s_waitcnt vmcnt(22)
	v_mov_b32_e32 v109, v25
	v_mov_b32_e32 v106, v32
	v_mov_b32_e32 v107, v24
	v_pk_mul_f32 v[108:109], v[108:109], v[108:109]
	v_mov_b32_e32 v102, v34
	v_mov_b32_e32 v103, v26
	v_pk_fma_f32 v[106:107], v[106:107], v[106:107], v[108:109]
	s_waitcnt vmcnt(20)
	v_mov_b32_e32 v122, v69
	s_waitcnt vmcnt(19)
	v_mov_b32_e32 v123, v41
	v_mov_b32_e32 v104, v35
	v_mov_b32_e32 v105, v27
	v_mov_b32_e32 v120, v68
	v_mov_b32_e32 v121, v40
	v_pk_fma_f32 v[102:103], v[102:103], v[102:103], v[106:107]
	v_pk_mul_f32 v[106:107], v[122:123], v[122:123]
	v_mov_b32_e32 v108, v70
	v_mov_b32_e32 v109, v42
	v_pk_fma_f32 v[102:103], v[104:105], v[104:105], v[102:103]
	v_pk_fma_f32 v[104:105], v[120:121], v[120:121], v[106:107]
	v_mov_b32_e32 v116, v29
	s_waitcnt vmcnt(18)
	v_mov_b32_e32 v117, v17
	v_pk_fma_f32 v[104:105], v[108:109], v[108:109], v[104:105]
	s_waitcnt vmcnt(17)
	v_mov_b32_e32 v108, v37
	s_waitcnt vmcnt(16)
	v_mov_b32_e32 v109, v21
	v_mov_b32_e32 v114, v28
	v_mov_b32_e32 v115, v16
	v_mov_b32_e32 v128, v36
	v_mov_b32_e32 v129, v20
	v_pk_mul_f32 v[116:117], v[116:117], v[116:117]
	v_pk_mul_f32 v[108:109], v[108:109], v[108:109]
	v_mov_b32_e32 v110, v30
	v_mov_b32_e32 v118, v71
	v_mov_b32_e32 v119, v43
	v_mov_b32_e32 v111, v18
	v_mov_b32_e32 v124, v38
	v_mov_b32_e32 v125, v22
	v_pk_fma_f32 v[106:107], v[114:115], v[114:115], v[116:117]
	v_pk_fma_f32 v[108:109], v[128:129], v[128:129], v[108:109]
	v_mov_b32_e32 v112, v31
	v_mov_b32_e32 v113, v19
	v_mov_b32_e32 v126, v39
	v_mov_b32_e32 v127, v23
	v_pk_fma_f32 v[106:107], v[110:111], v[110:111], v[106:107]
	v_pk_fma_f32 v[104:105], v[118:119], v[118:119], v[104:105]
	v_pk_fma_f32 v[108:109], v[124:125], v[124:125], v[108:109]
	v_pk_fma_f32 v[106:107], v[112:113], v[112:113], v[106:107]
	v_pk_fma_f32 v[108:109], v[126:127], v[126:127], v[108:109]
	v_mov_b32_e32 v110, v104
	v_mov_b32_e32 v111, v102
	v_mov_b32_e32 v102, v105
	v_pk_add_f32 v[102:103], v[110:111], v[102:103]
	v_mov_b32_e32 v104, v108
	v_mov_b32_e32 v105, v106
	v_pk_add_f32 v[102:103], v[102:103], v[104:105]
	v_mov_b32_e32 v106, v109
	v_pk_add_f32 v[102:103], v[102:103], v[106:107]
	ds_bpermute_b32 v105, v96, v103
	ds_bpermute_b32 v104, v96, v102
	s_waitcnt vmcnt(14)
	v_mov_b32_e32 v112, v81
	s_waitcnt vmcnt(13)
	v_mov_b32_e32 v113, v61
	v_mov_b32_e32 v110, v80
	v_mov_b32_e32 v111, v60
	s_waitcnt lgkmcnt(0)
	v_pk_add_f32 v[102:103], v[102:103], v[104:105]
	ds_bpermute_b32 v105, v97, v103
	ds_bpermute_b32 v104, v97, v102
	v_pk_mul_f32 v[112:113], v[112:113], v[112:113]
	v_mov_b32_e32 v106, v82
	v_mov_b32_e32 v107, v62
	v_pk_fma_f32 v[110:111], v[110:111], v[110:111], v[112:113]
	s_waitcnt lgkmcnt(0)
	v_pk_add_f32 v[102:103], v[102:103], v[104:105]
	ds_bpermute_b32 v105, v98, v103
	ds_bpermute_b32 v104, v98, v102
	s_waitcnt vmcnt(11)
	v_mov_b32_e32 v114, v77
	s_waitcnt vmcnt(10)
	v_mov_b32_e32 v115, v65
	v_mov_b32_e32 v108, v83
	v_mov_b32_e32 v109, v63
	s_waitcnt lgkmcnt(0)
	v_pk_add_f32 v[102:103], v[102:103], v[104:105]
	ds_bpermute_b32 v105, v99, v103
	ds_bpermute_b32 v104, v99, v102
	v_pk_fma_f32 v[106:107], v[106:107], v[106:107], v[110:111]
	v_mov_b32_e32 v112, v76
	v_mov_b32_e32 v113, v64
	v_pk_mul_f32 v[114:115], v[114:115], v[114:115]
	s_waitcnt lgkmcnt(0)
	v_pk_add_f32 v[102:103], v[102:103], v[104:105]
	ds_bpermute_b32 v105, v100, v103
	ds_bpermute_b32 v104, v100, v102
	v_pk_fma_f32 v[106:107], v[108:109], v[108:109], v[106:107]
	v_mov_b32_e32 v108, v78
	v_mov_b32_e32 v109, v66
	v_pk_fma_f32 v[112:113], v[112:113], v[112:113], v[114:115]
	s_waitcnt lgkmcnt(0)
	v_pk_add_f32 v[102:103], v[102:103], v[104:105]
	ds_bpermute_b32 v105, v101, v103
	ds_bpermute_b32 v104, v101, v102
	s_waitcnt vmcnt(8)
	v_mov_b32_e32 v114, v49
	s_waitcnt vmcnt(7)
	v_mov_b32_e32 v115, v53
	v_pk_fma_f32 v[108:109], v[108:109], v[108:109], v[112:113]
	v_mov_b32_e32 v112, v48
	v_mov_b32_e32 v113, v52
	v_pk_mul_f32 v[114:115], v[114:115], v[114:115]
	v_mov_b32_e32 v110, v79
	v_mov_b32_e32 v111, v67
	s_waitcnt lgkmcnt(0)
	v_pk_add_f32 v[102:103], v[102:103], v[104:105]
	v_mov_b32_e32 v104, v50
	v_mov_b32_e32 v105, v54
	v_pk_fma_f32 v[112:113], v[112:113], v[112:113], v[114:115]
	v_mov_b32_e32 v116, v45
	s_waitcnt vmcnt(6)
	v_mov_b32_e32 v117, v57
	v_pk_fma_f32 v[108:109], v[110:111], v[110:111], v[108:109]
	v_mov_b32_e32 v110, v51
	v_mov_b32_e32 v111, v55
	v_pk_fma_f32 v[104:105], v[104:105], v[104:105], v[112:113]
	v_mov_b32_e32 v114, v44
	v_mov_b32_e32 v115, v56
	v_pk_mul_f32 v[116:117], v[116:117], v[116:117]
	v_pk_fma_f32 v[104:105], v[110:111], v[110:111], v[104:105]
	v_mov_b32_e32 v110, v46
	v_mov_b32_e32 v111, v58
	v_pk_fma_f32 v[114:115], v[114:115], v[114:115], v[116:117]
	v_mov_b32_e32 v112, v47
	v_mov_b32_e32 v113, v59
	v_pk_fma_f32 v[110:111], v[110:111], v[110:111], v[114:115]
	v_pk_fma_f32 v[102:103], v[102:103], s[22:23], v[92:93] op_sel_hi:[1,0,0]
	v_pk_fma_f32 v[110:111], v[112:113], v[112:113], v[110:111]
	v_mov_b32_e32 v112, v108
	v_mov_b32_e32 v113, v106
	v_mov_b32_e32 v106, v109
	v_pk_add_f32 v[106:107], v[112:113], v[106:107]
	v_mov_b32_e32 v108, v110
	v_mov_b32_e32 v109, v104
	v_pk_add_f32 v[106:107], v[106:107], v[108:109]
	v_mov_b32_e32 v104, v111
	v_pk_add_f32 v[104:105], v[106:107], v[104:105]
	ds_bpermute_b32 v107, v96, v105
	ds_bpermute_b32 v106, v96, v104
	v_mul_f32_e32 v108, 0x4b800000, v103
	v_cmp_gt_f32_e32 vcc, s35, v103
	v_pk_add_f32 v[84:85], v[84:85], 1.0 op_sel_hi:[1,0]
	v_pk_add_f32 v[86:87], v[86:87], 1.0 op_sel_hi:[1,0]
	s_waitcnt lgkmcnt(0)
	v_pk_add_f32 v[104:105], v[104:105], v[106:107]
	ds_bpermute_b32 v107, v97, v105
	ds_bpermute_b32 v106, v97, v104
	v_cndmask_b32_e32 v103, v103, v108, vcc
	v_rsq_f32_e32 v103, v103
	v_pk_mul_f32 v[84:85], v[8:9], v[84:85]
	v_pk_mul_f32 v[86:87], v[10:11], v[86:87]
	s_waitcnt lgkmcnt(0)
	v_pk_add_f32 v[104:105], v[104:105], v[106:107]
	ds_bpermute_b32 v107, v98, v105
	ds_bpermute_b32 v106, v98, v104
	v_mul_f32_e32 v110, 0x45800000, v103
	v_cndmask_b32_e32 v110, v103, v110, vcc
	v_pk_mul_f32 v[32:33], v[32:33], v[110:111] op_sel_hi:[1,0]
	v_cmp_gt_f32_e32 vcc, s35, v102
	s_waitcnt lgkmcnt(0)
	v_pk_add_f32 v[104:105], v[104:105], v[106:107]
	ds_bpermute_b32 v107, v99, v105
	ds_bpermute_b32 v106, v99, v104
	v_pk_fma_f32 v[32:33], v[32:33], v[84:85], v[72:73]
	v_lshl_add_u64 v[108:109], s[30:31], 0, v[90:91]
	v_cvt_pk_bf16_f32 v32, v32, v33
	v_mul_f32_e32 v33, 0x4b800000, v102
	v_cndmask_b32_e32 v33, v102, v33, vcc
	v_rsq_f32_e32 v111, v33
	s_waitcnt lgkmcnt(0)
	v_pk_add_f32 v[102:103], v[104:105], v[106:107]
	ds_bpermute_b32 v105, v100, v103
	ds_bpermute_b32 v104, v100, v102
	v_pk_mul_f32 v[34:35], v[34:35], v[110:111] op_sel_hi:[1,0]
	v_mul_f32_e32 v106, 0x45800000, v111
	v_pk_fma_f32 v[34:35], v[34:35], v[86:87], v[74:75]
	v_pk_mul_f32 v[24:25], v[24:25], v[110:111] op_sel_hi:[1,0]
	v_cvt_pk_bf16_f32 v33, v34, v35
	s_waitcnt lgkmcnt(0)
	v_pk_add_f32 v[34:35], v[102:103], v[104:105]
	ds_bpermute_b32 v103, v101, v35
	ds_bpermute_b32 v102, v101, v34
	v_cndmask_b32_e32 v104, v111, v106, vcc
	v_pk_mul_f32 v[68:69], v[68:69], v[104:105] op_sel_hi:[1,0]
	v_pk_mul_f32 v[70:71], v[70:71], v[104:105] op_sel_hi:[1,0]
	v_pk_fma_f32 v[68:69], v[84:85], v[68:69], v[72:73]
	s_waitcnt lgkmcnt(0)
	v_pk_add_f32 v[34:35], v[34:35], v[102:103]
	v_cvt_pk_bf16_f32 v68, v68, v69
	v_pk_fma_f32 v[34:35], v[34:35], s[22:23], v[92:93] op_sel_hi:[1,0,0]
	v_pk_fma_f32 v[70:71], v[70:71], v[86:87], v[74:75]
	v_mul_f32_e32 v69, 0x4b800000, v35
	v_cmp_gt_f32_e32 vcc, s35, v35
	v_pk_mul_f32 v[26:27], v[26:27], v[110:111] op_sel_hi:[1,0]
	v_pk_mul_f32 v[40:41], v[40:41], v[104:105] op_sel_hi:[1,0]
	v_cndmask_b32_e32 v35, v35, v69, vcc
	v_rsq_f32_e32 v35, v35
	v_cvt_pk_bf16_f32 v69, v70, v71
	global_store_dwordx2 v90, v[32:33], s[30:31]
	global_store_dwordx2 v90, v[68:69], s[30:31] offset:2048
	v_pk_mul_f32 v[42:43], v[42:43], v[104:105] op_sel_hi:[1,0]
	v_mul_f32_e32 v70, 0x45800000, v35
	v_cndmask_b32_e32 v102, v35, v70, vcc
	v_mul_f32_e32 v35, 0x4b800000, v34
	v_cmp_gt_f32_e32 vcc, s35, v34
	v_pk_mul_f32 v[70:71], v[80:81], v[102:103] op_sel_hi:[1,0]
	v_pk_mul_f32 v[60:61], v[60:61], v[102:103] op_sel_hi:[1,0]
	v_cndmask_b32_e32 v34, v34, v35, vcc
	v_rsq_f32_e32 v80, v34
	v_pk_mul_f32 v[34:35], v[82:83], v[102:103] op_sel_hi:[1,0]
	v_pk_fma_f32 v[70:71], v[84:85], v[70:71], v[72:73]
	v_pk_fma_f32 v[34:35], v[86:87], v[34:35], v[74:75]
	v_cvt_pk_bf16_f32 v70, v70, v71
	v_cvt_pk_bf16_f32 v71, v34, v35
	v_mul_f32_e32 v34, 0x45800000, v80
	v_cndmask_b32_e32 v80, v80, v34, vcc
	v_pk_mul_f32 v[34:35], v[76:77], v[80:81] op_sel_hi:[1,0]
	v_add_co_u32_e32 v32, vcc, s11, v108
	v_pk_fma_f32 v[34:35], v[84:85], v[34:35], v[72:73]
	v_pk_mul_f32 v[72:73], v[78:79], v[80:81] op_sel_hi:[1,0]
	v_addc_co_u32_e32 v33, vcc, 0, v109, vcc
	v_pk_fma_f32 v[72:73], v[86:87], v[72:73], v[74:75]
	v_cvt_pk_bf16_f32 v34, v34, v35
	v_cvt_pk_bf16_f32 v35, v72, v73
	global_store_dwordx2 v[32:33], v[70:71], off
	global_store_dwordx2 v[32:33], v[34:35], off offset:2048
	s_nop 0
	v_pk_mul_f32 v[62:63], v[62:63], v[102:103] op_sel_hi:[1,0]
	v_lshl_add_u64 v[72:73], v[108:109], 0, s[2:3]
	v_pk_mul_f32 v[64:65], v[64:65], v[80:81] op_sel_hi:[1,0]
	v_pk_mul_f32 v[66:67], v[66:67], v[80:81] op_sel_hi:[1,0]
	v_lshl_add_u64 v[74:75], v[108:109], 0, s[12:13]
	v_pk_mul_f32 v[28:29], v[28:29], v[110:111] op_sel_hi:[1,0]
	v_pk_mul_f32 v[30:31], v[30:31], v[110:111] op_sel_hi:[1,0]
	v_pk_mul_f32 v[36:37], v[36:37], v[104:105] op_sel_hi:[1,0]
	v_pk_mul_f32 v[38:39], v[38:39], v[104:105] op_sel_hi:[1,0]
	v_pk_mul_f32 v[44:45], v[44:45], v[80:81] op_sel_hi:[1,0]
	v_pk_mul_f32 v[46:47], v[46:47], v[80:81] op_sel_hi:[1,0]
	v_pk_mul_f32 v[16:17], v[16:17], v[110:111] op_sel_hi:[1,0]
	v_pk_mul_f32 v[18:19], v[18:19], v[110:111] op_sel_hi:[1,0]
	v_pk_mul_f32 v[20:21], v[20:21], v[104:105] op_sel_hi:[1,0]
	v_pk_mul_f32 v[22:23], v[22:23], v[104:105] op_sel_hi:[1,0]
	s_waitcnt vmcnt(9)
	v_pk_add_f32 v[130:131], v[130:131], 1.0 op_sel_hi:[1,0]
	v_pk_add_f32 v[132:133], v[132:133], 1.0 op_sel_hi:[1,0]
	v_pk_mul_f32 v[130:131], v[0:1], v[130:131]
	v_pk_mul_f32 v[132:133], v[2:3], v[132:133]
	s_waitcnt vmcnt(8)
	v_pk_fma_f32 v[24:25], v[24:25], v[130:131], v[134:135]
	v_pk_fma_f32 v[26:27], v[26:27], v[132:133], v[136:137]
	v_cvt_pk_bf16_f32 v24, v24, v25
	v_cvt_pk_bf16_f32 v25, v26, v27
	global_store_dwordx2 v90, v[24:25], s[30:31] offset:512
	v_pk_fma_f32 v[24:25], v[40:41], v[130:131], v[134:135]
	v_pk_fma_f32 v[26:27], v[42:43], v[132:133], v[136:137]
	v_cvt_pk_bf16_f32 v24, v24, v25
	v_cvt_pk_bf16_f32 v25, v26, v27
	global_store_dwordx2 v90, v[24:25], s[30:31] offset:2560
	v_pk_fma_f32 v[24:25], v[60:61], v[130:131], v[134:135]
	v_pk_fma_f32 v[26:27], v[62:63], v[132:133], v[136:137]
	v_cvt_pk_bf16_f32 v24, v24, v25
	v_cvt_pk_bf16_f32 v25, v26, v27
	global_store_dwordx2 v[72:73], v[24:25], off offset:512
	v_pk_fma_f32 v[24:25], v[64:65], v[130:131], v[134:135]
	v_pk_fma_f32 v[26:27], v[66:67], v[132:133], v[136:137]
	v_cvt_pk_bf16_f32 v24, v24, v25
	v_cvt_pk_bf16_f32 v25, v26, v27
	global_store_dwordx2 v[74:75], v[24:25], off offset:512
	s_nop 0
	v_pk_mul_f32 v[40:41], v[48:49], v[102:103] op_sel_hi:[1,0]
	v_pk_mul_f32 v[42:43], v[50:51], v[102:103] op_sel_hi:[1,0]
	s_waitcnt vmcnt(11)
	v_pk_add_f32 v[138:139], v[138:139], 1.0 op_sel_hi:[1,0]
	v_pk_add_f32 v[140:141], v[140:141], 1.0 op_sel_hi:[1,0]
	v_pk_mul_f32 v[138:139], v[4:5], v[138:139]
	v_pk_mul_f32 v[140:141], v[6:7], v[140:141]
	s_waitcnt vmcnt(10)
	v_pk_fma_f32 v[28:29], v[28:29], v[138:139], v[142:143]
	v_pk_fma_f32 v[30:31], v[30:31], v[140:141], v[144:145]
	v_cvt_pk_bf16_f32 v28, v28, v29
	v_cvt_pk_bf16_f32 v29, v30, v31
	global_store_dwordx2 v90, v[28:29], s[30:31] offset:1024
	v_pk_fma_f32 v[28:29], v[36:37], v[138:139], v[142:143]
	v_pk_fma_f32 v[30:31], v[38:39], v[140:141], v[144:145]
	v_cvt_pk_bf16_f32 v28, v28, v29
	v_cvt_pk_bf16_f32 v29, v30, v31
	global_store_dwordx2 v90, v[28:29], s[30:31] offset:3072
	v_pk_fma_f32 v[28:29], v[40:41], v[138:139], v[142:143]
	v_pk_fma_f32 v[30:31], v[42:43], v[140:141], v[144:145]
	v_pk_fma_f32 v[138:139], v[44:45], v[138:139], v[142:143]
	v_pk_fma_f32 v[140:141], v[46:47], v[140:141], v[144:145]
	v_cvt_pk_bf16_f32 v28, v28, v29
	v_cvt_pk_bf16_f32 v29, v30, v31
	v_cvt_pk_bf16_f32 v138, v138, v139
	v_cvt_pk_bf16_f32 v139, v140, v141
	global_store_dwordx2 v[72:73], v[28:29], off offset:1024
	global_store_dwordx2 v[74:75], v[138:139], off offset:1024
	s_nop 0
	v_pk_mul_f32 v[32:33], v[52:53], v[102:103] op_sel_hi:[1,0]
	v_pk_mul_f32 v[34:35], v[54:55], v[102:103] op_sel_hi:[1,0]
	v_pk_mul_f32 v[36:37], v[56:57], v[80:81] op_sel_hi:[1,0]
	v_pk_mul_f32 v[38:39], v[58:59], v[80:81] op_sel_hi:[1,0]
	s_waitcnt vmcnt(13)
	v_pk_add_f32 v[146:147], v[146:147], 1.0 op_sel_hi:[1,0]
	v_pk_add_f32 v[148:149], v[148:149], 1.0 op_sel_hi:[1,0]
	v_pk_mul_f32 v[146:147], v[12:13], v[146:147]
	v_pk_mul_f32 v[148:149], v[14:15], v[148:149]
	s_waitcnt vmcnt(12)
	v_pk_fma_f32 v[16:17], v[16:17], v[146:147], v[150:151]
	v_pk_fma_f32 v[18:19], v[18:19], v[148:149], v[152:153]
	v_pk_fma_f32 v[20:21], v[20:21], v[146:147], v[150:151]
	v_pk_fma_f32 v[22:23], v[22:23], v[148:149], v[152:153]
	v_pk_fma_f32 v[32:33], v[32:33], v[146:147], v[150:151]
	v_pk_fma_f32 v[34:35], v[34:35], v[148:149], v[152:153]
	v_pk_fma_f32 v[146:147], v[36:37], v[146:147], v[150:151]
	v_pk_fma_f32 v[148:149], v[38:39], v[148:149], v[152:153]
	v_cvt_pk_bf16_f32 v16, v16, v17
	v_cvt_pk_bf16_f32 v17, v18, v19
	v_cvt_pk_bf16_f32 v18, v20, v21
	v_cvt_pk_bf16_f32 v19, v22, v23
	v_cvt_pk_bf16_f32 v20, v32, v33
	v_cvt_pk_bf16_f32 v21, v34, v35
	v_cvt_pk_bf16_f32 v22, v146, v147
	v_cvt_pk_bf16_f32 v23, v148, v149
	global_store_dwordx2 v90, v[16:17], s[30:31] offset:1536
	global_store_dwordx2 v90, v[18:19], s[30:31] offset:3584
	global_store_dwordx2 v[72:73], v[20:21], off offset:1536
	global_store_dwordx2 v[74:75], v[22:23], off offset:1536
	s_cbranch_scc0 .LBB0_877

.LBB0_1311:
	s_mul_hi_i32 s1, s0, 0x38e38e39
	s_lshr_b32 s2, s1, 31
	s_ashr_i32 s1, s1, 9
	s_add_i32 s38, s1, s2
	s_mul_i32 s1, s38, 0xfffff700
	s_add_i32 s1, s0, s1
	s_cmpk_lt_i32 s1, 0x100
	s_cbranch_scc1 .LBB0_1310
	s_ashr_i32 s39, s38, 31
	s_add_i32 s2, s1, 0xffffff00
	s_lshl_b64 s[40:41], s[38:39], 23
	s_add_u32 s1, s66, s40
	s_addc_u32 s39, s67, s41
	s_lshl_b64 s[40:41], s[2:3], 12
	s_add_u32 s40, s1, s40
	s_addc_u32 s41, s39, s41
	v_lshl_add_u64 v[28:29], s[40:41], 0, v[76:77]
	global_load_dwordx4 v[16:19], v76, s[40:41]
	global_load_dwordx4 v[0:3], v76, s[40:41] offset:1024
	v_add_co_u32_e32 v30, vcc, s35, v28
	s_mul_i32 s2, s38, 0x6000
	s_nop 0
	v_addc_co_u32_e32 v31, vcc, 0, v29, vcc
	s_waitcnt lgkmcnt(0)
	global_load_dwordx4 v[8:11], v76, s[40:41] offset:2048
	v_lshl_add_u64 v[12:13], v[28:29], 0, s[4:5]
	global_load_dwordx4 v[48:51], v[30:31], off offset:-4096
	global_load_dwordx4 v[24:27], v[12:13], off offset:1024
	s_mul_hi_i32 s1, s38, 0x6000
	s_add_u32 s38, s20, s2
	s_addc_u32 s39, s21, s1
	global_load_dwordx4 v[4:7], v76, s[40:41] offset:3072
	v_lshl_add_u64 v[82:83], s[38:39], 0, v[76:77]
	v_add_co_u32_e32 v14, vcc, s31, v82
	v_lshl_add_u64 v[52:53], v[28:29], 0, s[6:7]
	s_nop 0
	v_addc_co_u32_e32 v15, vcc, 0, v83, vcc
	global_load_dwordx4 v[64:67], v[14:15], off
	global_load_dwordx4 v[68:71], v[78:79], off
	global_load_dwordx4 v[20:23], v[12:13], off offset:2048
	s_nop 0
	global_load_dwordx4 v[12:15], v[12:13], off offset:3072
	s_nop 0
	global_load_dwordx4 v[40:43], v[52:53], off offset:1024
	global_load_dwordx4 v[36:39], v[78:79], off offset:1024
	global_load_dwordx4 v[60:63], v[30:31], off
	v_lshl_add_u64 v[92:93], v[28:29], 0, s[8:9]
	v_add_co_u32_e32 v28, vcc, s37, v28
	v_readlane_b32 s44, v239, 32
	s_nop 0
	v_addc_co_u32_e32 v29, vcc, 0, v29, vcc
	global_load_dwordx4 v[56:59], v[28:29], off
	global_load_dwordx4 v[44:47], v[92:93], off offset:1024
	s_nop 0
	global_load_dwordx4 v[28:31], v[92:93], off offset:2048
	global_load_dwordx4 v[32:35], v[52:53], off offset:2048
	s_nop 0
	global_load_dwordx4 v[52:55], v[52:53], off offset:3072
	v_add_co_u32_e32 v72, vcc, s33, v82
	s_ashr_i32 s1, s0, 31
	s_nop 0
	v_addc_co_u32_e32 v73, vcc, 0, v83, vcc
	global_load_dwordx4 v[72:75], v[72:73], off
	v_readlane_b32 s45, v239, 33
	s_lshl_b64 s[38:39], s[0:1], 11
	s_mov_b64 s[40:41], s[44:45]
	s_add_u32 s38, s40, s38
	s_addc_u32 s39, s41, s39
	v_lshl_add_u64 v[84:85], v[82:83], 0, s[12:13]
	v_readlane_b32 s46, v239, 34
	v_readlane_b32 s47, v239, 35
	v_readlane_b32 s48, v239, 36
	v_readlane_b32 s49, v239, 37
	v_readlane_b32 s50, v239, 38
	v_readlane_b32 s51, v239, 39
	global_load_dwordx4 v[120:123], v[84:85], off offset:1024
	v_lshl_add_u64 v[124:125], v[82:83], 0, s[22:23]
	global_load_dwordx4 v[126:129], v[124:125], off offset:1024
	global_load_dwordx4 v[130:133], v[84:85], off offset:2048
	global_load_dwordx4 v[134:137], v[78:79], off offset:2048
	global_load_dwordx4 v[138:141], v[124:125], off offset:2048
	global_load_dwordx4 v[142:145], v[78:79], off offset:3072
	global_load_dwordx4 v[146:149], v[84:85], off offset:3072
	global_load_dwordx4 v[150:153], v[124:125], off offset:3072
	s_waitcnt vmcnt(26)
	v_mov_b32_e32 v100, v17
	s_waitcnt vmcnt(25)
	v_mov_b32_e32 v101, v1
	v_mov_b32_e32 v98, v16
	v_mov_b32_e32 v99, v0
	v_pk_mul_f32 v[100:101], v[100:101], v[100:101]
	v_mov_b32_e32 v94, v18
	v_mov_b32_e32 v95, v2
	v_pk_fma_f32 v[98:99], v[98:99], v[98:99], v[100:101]
	s_waitcnt vmcnt(23)
	v_mov_b32_e32 v114, v49
	s_waitcnt vmcnt(22)
	v_mov_b32_e32 v115, v25
	v_mov_b32_e32 v112, v48
	v_mov_b32_e32 v113, v24
	v_pk_fma_f32 v[94:95], v[94:95], v[94:95], v[98:99]
	v_pk_mul_f32 v[98:99], v[114:115], v[114:115]
	v_mov_b32_e32 v108, v9
	v_mov_b32_e32 v100, v50
	v_mov_b32_e32 v101, v26
	s_waitcnt vmcnt(21)
	v_mov_b32_e32 v109, v5
	s_waitcnt vmcnt(20)
	v_pk_add_f32 v[114:115], v[64:65], 1.0 op_sel_hi:[1,0]
	v_pk_fma_f32 v[64:65], v[112:113], v[112:113], v[98:99]
	v_mov_b32_e32 v96, v19
	v_mov_b32_e32 v97, v3
	v_mov_b32_e32 v106, v8
	v_mov_b32_e32 v110, v51
	v_mov_b32_e32 v111, v27
	v_mov_b32_e32 v107, v4
	v_pk_mul_f32 v[108:109], v[108:109], v[108:109]
	v_pk_fma_f32 v[64:65], v[100:101], v[100:101], v[64:65]
	v_mov_b32_e32 v102, v10
	v_mov_b32_e32 v103, v6
	v_pk_add_f32 v[66:67], v[66:67], 1.0 op_sel_hi:[1,0]
	v_pk_fma_f32 v[94:95], v[96:97], v[96:97], v[94:95]
	v_pk_fma_f32 v[96:97], v[110:111], v[110:111], v[64:65]
	v_pk_fma_f32 v[64:65], v[106:107], v[106:107], v[108:109]
	s_waitcnt vmcnt(19)
	v_pk_mul_f32 v[70:71], v[70:71], v[66:67]
	v_pk_fma_f32 v[98:99], v[102:103], v[102:103], v[64:65]
	global_load_dwordx4 v[64:67], v[92:93], off offset:3072
	v_mov_b32_e32 v104, v11
	v_mov_b32_e32 v105, v7
	v_pk_fma_f32 v[92:93], v[104:105], v[104:105], v[98:99]
	s_waitcnt vmcnt(19)
	v_mov_b32_e32 v104, v21
	s_waitcnt vmcnt(18)
	v_mov_b32_e32 v105, v13
	v_mov_b32_e32 v102, v20
	v_mov_b32_e32 v103, v12
	v_pk_mul_f32 v[104:105], v[104:105], v[104:105]
	v_mov_b32_e32 v98, v22
	v_mov_b32_e32 v99, v14
	v_pk_fma_f32 v[102:103], v[102:103], v[102:103], v[104:105]
	v_mov_b32_e32 v100, v23
	v_mov_b32_e32 v101, v15
	v_pk_fma_f32 v[98:99], v[98:99], v[98:99], v[102:103]
	s_waitcnt vmcnt(15)
	v_mov_b32_e32 v102, v61
	v_pk_fma_f32 v[98:99], v[100:101], v[100:101], v[98:99]
	v_mov_b32_e32 v100, v96
	v_mov_b32_e32 v101, v94
	v_mov_b32_e32 v94, v97
	v_pk_add_f32 v[94:95], v[100:101], v[94:95]
	v_mov_b32_e32 v96, v98
	v_mov_b32_e32 v97, v92
	v_pk_add_f32 v[94:95], v[94:95], v[96:97]
	v_mov_b32_e32 v92, v99
	v_pk_add_f32 v[92:93], v[94:95], v[92:93]
	ds_bpermute_b32 v95, v86, v93
	ds_bpermute_b32 v94, v86, v92
	v_mov_b32_e32 v103, v41
	v_mov_b32_e32 v100, v60
	v_mov_b32_e32 v101, v40
	v_pk_mul_f32 v[102:103], v[102:103], v[102:103]
	s_waitcnt lgkmcnt(0)
	v_pk_add_f32 v[92:93], v[92:93], v[94:95]
	ds_bpermute_b32 v95, v87, v93
	ds_bpermute_b32 v94, v87, v92
	v_mov_b32_e32 v96, v62
	v_mov_b32_e32 v97, v42
	v_pk_fma_f32 v[100:101], v[100:101], v[100:101], v[102:103]
	s_waitcnt vmcnt(14)
	v_mov_b32_e32 v104, v57
	s_waitcnt lgkmcnt(0)
	v_pk_add_f32 v[92:93], v[92:93], v[94:95]
	ds_bpermute_b32 v95, v88, v93
	ds_bpermute_b32 v94, v88, v92
	s_waitcnt vmcnt(13)
	v_mov_b32_e32 v105, v45
	v_mov_b32_e32 v98, v63
	v_mov_b32_e32 v99, v43
	v_pk_fma_f32 v[96:97], v[96:97], v[96:97], v[100:101]
	v_mov_b32_e32 v102, v56
	v_mov_b32_e32 v103, v44
	v_pk_mul_f32 v[104:105], v[104:105], v[104:105]
	v_pk_fma_f32 v[96:97], v[98:99], v[98:99], v[96:97]
	v_mov_b32_e32 v98, v58
	v_mov_b32_e32 v99, v46
	v_pk_fma_f32 v[102:103], v[102:103], v[102:103], v[104:105]
	s_waitcnt vmcnt(11)
	v_mov_b32_e32 v106, v33
	s_waitcnt vmcnt(10)
	v_mov_b32_e32 v107, v53
	v_mov_b32_e32 v100, v59
	v_mov_b32_e32 v101, v47
	v_pk_fma_f32 v[98:99], v[98:99], v[98:99], v[102:103]
	v_mov_b32_e32 v104, v32
	v_mov_b32_e32 v105, v52
	v_pk_mul_f32 v[106:107], v[106:107], v[106:107]
	s_waitcnt lgkmcnt(0)
	v_pk_add_f32 v[92:93], v[92:93], v[94:95]
	v_pk_fma_f32 v[98:99], v[100:101], v[100:101], v[98:99]
	v_mov_b32_e32 v100, v34
	v_mov_b32_e32 v101, v54
	v_pk_fma_f32 v[104:105], v[104:105], v[104:105], v[106:107]
	v_mov_b32_e32 v108, v29
	ds_bpermute_b32 v95, v89, v93
	ds_bpermute_b32 v94, v89, v92
	v_mov_b32_e32 v102, v35
	v_mov_b32_e32 v103, v55
	v_pk_fma_f32 v[100:101], v[100:101], v[100:101], v[104:105]
	v_mov_b32_e32 v106, v28
	v_pk_fma_f32 v[100:101], v[102:103], v[102:103], v[100:101]
	v_mov_b32_e32 v102, v30
	v_mov_b32_e32 v104, v31
	s_waitcnt lgkmcnt(0)
	v_pk_add_f32 v[92:93], v[92:93], v[94:95]
	ds_bpermute_b32 v95, v90, v93
	ds_bpermute_b32 v94, v90, v92
	v_pk_mul_f32 v[68:69], v[68:69], v[114:115]
	s_waitcnt vmcnt(0)
	v_mov_b32_e32 v109, v65
	v_mov_b32_e32 v107, v64
	v_pk_mul_f32 v[108:109], v[108:109], v[108:109]
	v_mov_b32_e32 v103, v66
	v_pk_fma_f32 v[106:107], v[106:107], v[106:107], v[108:109]
	v_mov_b32_e32 v105, v67
	v_pk_fma_f32 v[102:103], v[102:103], v[102:103], v[106:107]
	s_waitcnt lgkmcnt(0)
	v_pk_add_f32 v[92:93], v[92:93], v[94:95]
	v_pk_fma_f32 v[102:103], v[104:105], v[104:105], v[102:103]
	v_mov_b32_e32 v104, v98
	v_mov_b32_e32 v105, v96
	v_mov_b32_e32 v96, v99
	v_pk_add_f32 v[96:97], v[104:105], v[96:97]
	v_mov_b32_e32 v98, v102
	v_mov_b32_e32 v99, v100
	v_pk_add_f32 v[96:97], v[96:97], v[98:99]
	v_mov_b32_e32 v100, v103
	v_pk_add_f32 v[96:97], v[96:97], v[100:101]
	ds_bpermute_b32 v99, v86, v97
	ds_bpermute_b32 v98, v86, v96
	ds_bpermute_b32 v95, v91, v93
	ds_bpermute_b32 v94, v91, v92
	s_waitcnt lgkmcnt(2)
	v_pk_add_f32 v[96:97], v[96:97], v[98:99]
	ds_bpermute_b32 v99, v87, v97
	ds_bpermute_b32 v98, v87, v96
	s_waitcnt lgkmcnt(2)
	v_pk_add_f32 v[92:93], v[92:93], v[94:95]
	v_mov_b64_e32 v[94:95], s[36:37]
	v_pk_fma_f32 v[92:93], v[92:93], s[30:31], v[94:95] op_sel_hi:[1,0,0]
	s_waitcnt lgkmcnt(0)
	v_pk_add_f32 v[96:97], v[96:97], v[98:99]
	v_mul_f32_e32 v81, 0x4b800000, v93
	v_cmp_gt_f32_e32 vcc, s42, v93
	ds_bpermute_b32 v99, v88, v97
	ds_bpermute_b32 v98, v88, v96
	v_cndmask_b32_e32 v81, v93, v81, vcc
	v_rsq_f32_e32 v93, v81
	v_mov_b32_e32 v81, v77
	v_lshl_add_u64 v[100:101], s[38:39], 0, v[80:81]
	s_waitcnt lgkmcnt(0)
	v_pk_add_f32 v[96:97], v[96:97], v[98:99]
	v_mul_f32_e32 v81, 0x45800000, v93
	ds_bpermute_b32 v99, v89, v97
	ds_bpermute_b32 v98, v89, v96
	v_cndmask_b32_e32 v102, v93, v81, vcc
	v_pk_mul_f32 v[16:17], v[16:17], v[102:103] op_sel_hi:[1,0]
	v_cmp_gt_f32_e32 vcc, s42, v92
	v_pk_fma_f32 v[16:17], v[16:17], v[68:69], v[72:73]
	v_pk_mul_f32 v[18:19], v[18:19], v[102:103] op_sel_hi:[1,0]
	v_cvt_pk_bf16_f32 v16, v16, v17
	v_mul_f32_e32 v17, 0x4b800000, v92
	v_cndmask_b32_e32 v17, v92, v17, vcc
	s_waitcnt lgkmcnt(0)
	v_pk_add_f32 v[92:93], v[96:97], v[98:99]
	ds_bpermute_b32 v97, v90, v93
	ds_bpermute_b32 v96, v90, v92
	v_pk_fma_f32 v[18:19], v[18:19], v[70:71], v[74:75]
	v_rsq_f32_e32 v81, v17
	v_cvt_pk_bf16_f32 v17, v18, v19
	v_pk_mul_f32 v[0:1], v[0:1], v[102:103] op_sel_hi:[1,0]
	s_waitcnt lgkmcnt(0)
	v_pk_add_f32 v[18:19], v[92:93], v[96:97]
	ds_bpermute_b32 v93, v91, v19
	ds_bpermute_b32 v92, v91, v18
	v_mul_f32_e32 v98, 0x45800000, v81
	v_cndmask_b32_e32 v96, v81, v98, vcc
	v_pk_mul_f32 v[48:49], v[48:49], v[96:97] op_sel_hi:[1,0]
	v_pk_mul_f32 v[50:51], v[50:51], v[96:97] op_sel_hi:[1,0]
	s_waitcnt lgkmcnt(0)
	v_pk_add_f32 v[18:19], v[18:19], v[92:93]
	v_pk_fma_f32 v[48:49], v[68:69], v[48:49], v[72:73]
	v_pk_fma_f32 v[18:19], v[18:19], s[30:31], v[94:95] op_sel_hi:[1,0,0]
	v_cvt_pk_bf16_f32 v48, v48, v49
	v_mul_f32_e32 v49, 0x4b800000, v19
	v_cmp_gt_f32_e32 vcc, s42, v19
	v_pk_fma_f32 v[50:51], v[50:51], v[70:71], v[74:75]
	v_pk_mul_f32 v[2:3], v[2:3], v[102:103] op_sel_hi:[1,0]
	v_cndmask_b32_e32 v19, v19, v49, vcc
	v_rsq_f32_e32 v19, v19
	v_cvt_pk_bf16_f32 v49, v50, v51
	global_store_dwordx2 v80, v[16:17], s[38:39]
	global_store_dwordx2 v80, v[48:49], s[38:39] offset:2048
	v_pk_mul_f32 v[24:25], v[24:25], v[96:97] op_sel_hi:[1,0]
	v_mul_f32_e32 v50, 0x45800000, v19
	v_cndmask_b32_e32 v92, v19, v50, vcc
	v_mul_f32_e32 v19, 0x4b800000, v18
	v_cmp_gt_f32_e32 vcc, s42, v18
	v_pk_mul_f32 v[50:51], v[60:61], v[92:93] op_sel_hi:[1,0]
	v_pk_mul_f32 v[26:27], v[26:27], v[96:97] op_sel_hi:[1,0]
	v_cndmask_b32_e32 v18, v18, v19, vcc
	v_rsq_f32_e32 v60, v18
	v_pk_mul_f32 v[18:19], v[62:63], v[92:93] op_sel_hi:[1,0]
	v_pk_fma_f32 v[50:51], v[68:69], v[50:51], v[72:73]
	v_pk_fma_f32 v[18:19], v[70:71], v[18:19], v[74:75]
	v_cvt_pk_bf16_f32 v50, v50, v51
	v_cvt_pk_bf16_f32 v51, v18, v19
	v_mul_f32_e32 v18, 0x45800000, v60
	v_cndmask_b32_e32 v60, v60, v18, vcc
	v_pk_mul_f32 v[18:19], v[56:57], v[60:61] op_sel_hi:[1,0]
	v_pk_mul_f32 v[56:57], v[58:59], v[60:61] op_sel_hi:[1,0]
	v_add_co_u32_e32 v16, vcc, s34, v100
	v_pk_fma_f32 v[18:19], v[68:69], v[18:19], v[72:73]
	v_pk_fma_f32 v[56:57], v[70:71], v[56:57], v[74:75]
	v_addc_co_u32_e32 v17, vcc, 0, v101, vcc
	v_cvt_pk_bf16_f32 v18, v18, v19
	v_cvt_pk_bf16_f32 v19, v56, v57
	global_store_dwordx2 v[16:17], v[50:51], off
	global_store_dwordx2 v[16:17], v[18:19], off offset:2048
	v_lshl_add_u64 v[56:57], v[82:83], 0, s[22:23]
	v_pk_mul_f32 v[40:41], v[40:41], v[92:93] op_sel_hi:[1,0]
	v_pk_mul_f32 v[42:43], v[42:43], v[92:93] op_sel_hi:[1,0]
	v_lshl_add_u64 v[58:59], v[100:101], 0, s[4:5]
	v_pk_mul_f32 v[44:45], v[44:45], v[60:61] op_sel_hi:[1,0]
	v_pk_mul_f32 v[46:47], v[46:47], v[60:61] op_sel_hi:[1,0]
	v_lshl_add_u64 v[62:63], v[100:101], 0, s[24:25]
	v_pk_mul_f32 v[8:9], v[8:9], v[102:103] op_sel_hi:[1,0]
	v_pk_mul_f32 v[10:11], v[10:11], v[102:103] op_sel_hi:[1,0]
	v_pk_mul_f32 v[20:21], v[20:21], v[96:97] op_sel_hi:[1,0]
	v_pk_mul_f32 v[22:23], v[22:23], v[96:97] op_sel_hi:[1,0]
	v_pk_mul_f32 v[32:33], v[32:33], v[92:93] op_sel_hi:[1,0]
	v_pk_mul_f32 v[34:35], v[34:35], v[92:93] op_sel_hi:[1,0]
	v_pk_mul_f32 v[28:29], v[28:29], v[60:61] op_sel_hi:[1,0]
	v_pk_mul_f32 v[30:31], v[30:31], v[60:61] op_sel_hi:[1,0]
	v_pk_mul_f32 v[4:5], v[4:5], v[102:103] op_sel_hi:[1,0]
	v_pk_mul_f32 v[6:7], v[6:7], v[102:103] op_sel_hi:[1,0]
	v_pk_mul_f32 v[12:13], v[12:13], v[96:97] op_sel_hi:[1,0]
	v_pk_mul_f32 v[14:15], v[14:15], v[96:97] op_sel_hi:[1,0]
	v_pk_add_f32 v[120:121], v[120:121], 1.0 op_sel_hi:[1,0]
	v_pk_add_f32 v[122:123], v[122:123], 1.0 op_sel_hi:[1,0]
	v_pk_mul_f32 v[120:121], v[36:37], v[120:121]
	v_pk_mul_f32 v[122:123], v[38:39], v[122:123]
	v_pk_fma_f32 v[0:1], v[0:1], v[120:121], v[126:127]
	v_pk_fma_f32 v[2:3], v[2:3], v[122:123], v[128:129]
	v_cvt_pk_bf16_f32 v0, v0, v1
	v_cvt_pk_bf16_f32 v1, v2, v3
	global_store_dwordx2 v80, v[0:1], s[38:39] offset:512
	v_pk_fma_f32 v[0:1], v[24:25], v[120:121], v[126:127]
	v_pk_fma_f32 v[2:3], v[26:27], v[122:123], v[128:129]
	v_cvt_pk_bf16_f32 v0, v0, v1
	v_cvt_pk_bf16_f32 v1, v2, v3
	global_store_dwordx2 v80, v[0:1], s[38:39] offset:2560
	v_pk_fma_f32 v[0:1], v[40:41], v[120:121], v[126:127]
	v_pk_fma_f32 v[2:3], v[42:43], v[122:123], v[128:129]
	v_cvt_pk_bf16_f32 v0, v0, v1
	v_cvt_pk_bf16_f32 v1, v2, v3
	global_store_dwordx2 v[58:59], v[0:1], off offset:512
	v_pk_fma_f32 v[0:1], v[44:45], v[120:121], v[126:127]
	v_pk_fma_f32 v[2:3], v[46:47], v[122:123], v[128:129]
	v_cvt_pk_bf16_f32 v0, v0, v1
	v_cvt_pk_bf16_f32 v1, v2, v3
	global_store_dwordx2 v[62:63], v[0:1], off offset:512
	s_nop 0
	v_pk_add_f32 v[130:131], v[130:131], 1.0 op_sel_hi:[1,0]
	v_pk_add_f32 v[132:133], v[132:133], 1.0 op_sel_hi:[1,0]
	v_pk_mul_f32 v[130:131], v[134:135], v[130:131]
	v_pk_mul_f32 v[132:133], v[136:137], v[132:133]
	v_pk_fma_f32 v[8:9], v[8:9], v[130:131], v[138:139]
	v_pk_fma_f32 v[10:11], v[10:11], v[132:133], v[140:141]
	v_cvt_pk_bf16_f32 v8, v8, v9
	v_cvt_pk_bf16_f32 v9, v10, v11
	global_store_dwordx2 v80, v[8:9], s[38:39] offset:1024
	v_pk_fma_f32 v[8:9], v[20:21], v[130:131], v[138:139]
	v_pk_fma_f32 v[10:11], v[22:23], v[132:133], v[140:141]
	v_cvt_pk_bf16_f32 v8, v8, v9
	v_cvt_pk_bf16_f32 v9, v10, v11
	global_store_dwordx2 v80, v[8:9], s[38:39] offset:3072
	v_pk_fma_f32 v[8:9], v[32:33], v[130:131], v[138:139]
	v_pk_fma_f32 v[10:11], v[34:35], v[132:133], v[140:141]
	v_pk_fma_f32 v[130:131], v[28:29], v[130:131], v[138:139]
	v_pk_fma_f32 v[132:133], v[30:31], v[132:133], v[140:141]
	v_cvt_pk_bf16_f32 v8, v8, v9
	v_cvt_pk_bf16_f32 v9, v10, v11
	v_cvt_pk_bf16_f32 v130, v130, v131
	v_cvt_pk_bf16_f32 v131, v132, v133
	global_store_dwordx2 v[58:59], v[8:9], off offset:1024
	global_store_dwordx2 v[62:63], v[130:131], off offset:1024
	s_nop 0
	v_pk_mul_f32 v[16:17], v[52:53], v[92:93] op_sel_hi:[1,0]
	v_pk_mul_f32 v[18:19], v[54:55], v[92:93] op_sel_hi:[1,0]
	v_pk_mul_f32 v[20:21], v[64:65], v[60:61] op_sel_hi:[1,0]
	v_pk_mul_f32 v[22:23], v[66:67], v[60:61] op_sel_hi:[1,0]
	v_pk_add_f32 v[146:147], v[146:147], 1.0 op_sel_hi:[1,0]
	v_pk_add_f32 v[148:149], v[148:149], 1.0 op_sel_hi:[1,0]
	v_pk_mul_f32 v[146:147], v[142:143], v[146:147]
	v_pk_mul_f32 v[148:149], v[144:145], v[148:149]
	v_pk_fma_f32 v[4:5], v[4:5], v[146:147], v[150:151]
	v_pk_fma_f32 v[6:7], v[6:7], v[148:149], v[152:153]
	v_pk_fma_f32 v[12:13], v[12:13], v[146:147], v[150:151]
	v_pk_fma_f32 v[14:15], v[14:15], v[148:149], v[152:153]
	v_pk_fma_f32 v[16:17], v[16:17], v[146:147], v[150:151]
	v_pk_fma_f32 v[18:19], v[18:19], v[148:149], v[152:153]
	v_pk_fma_f32 v[146:147], v[20:21], v[146:147], v[150:151]
	v_pk_fma_f32 v[148:149], v[22:23], v[148:149], v[152:153]
	v_cvt_pk_bf16_f32 v4, v4, v5
	v_cvt_pk_bf16_f32 v5, v6, v7
	v_cvt_pk_bf16_f32 v6, v12, v13
	v_cvt_pk_bf16_f32 v7, v14, v15
	v_cvt_pk_bf16_f32 v8, v16, v17
	v_cvt_pk_bf16_f32 v9, v18, v19
	v_cvt_pk_bf16_f32 v146, v146, v147
	v_cvt_pk_bf16_f32 v147, v148, v149
	global_store_dwordx2 v80, v[4:5], s[38:39] offset:1536
	global_store_dwordx2 v80, v[6:7], s[38:39] offset:3584
	global_store_dwordx2 v[58:59], v[8:9], off offset:1536
	global_store_dwordx2 v[62:63], v[146:147], off offset:1536
	s_branch .LBB0_1310
